# cross attention without the L2 warm-up loads (after the XCD-local unit remap the K/V stages of a batch are already shared inside the XCD)
# speedup vs baseline: 1.0076x; 1.0047x over previous
; #define LAS __attribute__((address_space(3)))
; #define DSEC(k) do { if (PROBE_DSEC) { const unsigned long long tn_ = __builtin_amdgcn_s_memrealtime(); if (PROBE_DSEC == (k)) tsec += tn_ - tl_; tl_ = tn_; } } while (0)
; #define XK_WRITE(R) do { _Pragma("unroll") for (int i = 0; i < 8; ++i) { const int p = tid + 512 * i, m = p >> 4, cb = p & 15; *(LAS u32x4*)(KL + m * KSTR + 16 * cb) = R[i]; } } while (0)
; DI void xattn_phase(LAS unsigned char* L, const bf16* Qx, const bf16* memK, const bf16* memVT, bf16* Ox, int G, int bid, int tid, unsigned long long& tsec) {
;     unsigned long long tl_ = PROBE_DSEC ? __builtin_amdgcn_s_memrealtime() : 0;
;     const int wid = __builtin_amdgcn_readfirstlane(tid >> 6), lane = tid & 63, fr = lane & 15, fq = lane >> 4;
;     LAS unsigned char* KL = L; LAS unsigned char* VL = L + KL_BYTES;
;     u32x4 ra[8], rb[8];
;     if (bid < 512) { const int h0 = (bid >> 5) & 3, b0 = bid >> 7; XK_LOAD(ra, b0, h0, 0); XV_LOAD(rb, b0, h0, 0); }
;     for (int unit = bid; unit < 512; unit += G) {
;         const int j = unit & 31, h = (unit >> 5) & 3, b = unit >> 7;
;         const int nun = unit + G < 512 ? unit + G : unit, hn = (nun >> 5) & 3, bn = nun >> 7;
;         asm volatile("" : "+v"(ra[0]), "+v"(ra[1]), "+v"(ra[2]), "+v"(ra[3]), "+v"(ra[4]), "+v"(ra[5]), "+v"(ra[6]), "+v"(ra[7]));
;         asm volatile("" : "+v"(rb[0]), "+v"(rb[1]), "+v"(rb[2]), "+v"(rb[3]), "+v"(rb[4]), "+v"(rb[5]), "+v"(rb[6]), "+v"(rb[7]));
;         const int tok0 = b * T + 128 * j; const size_t tq = (size_t)(tok0 + 16 * wid + fr);
;         f32x4 s[16];
; #pragma unroll
;         for (int kt = 0; kt < 16; ++kt) s[kt] = (f32x4){0.f, 0.f, 0.f, 0.f};
; #pragma unroll
;         for (int hh = 0; hh < 2; ++hh) {
;             __syncthreads();
;             XK_WRITE(ra);
;             if (hh == 0) { XV_WRITE(rb); XK_LOAD(ra, b, h, 1); XV_LOAD(rb, b, h, 1); }
;             else XK_LOAD(ra, bn, hn, 0);
;             __syncthreads();
;             DSEC(11);
; #pragma unroll
;             for (int k4 = 0; k4 < 4; ++k4) { const bf16x8 qk = *(const bf16x8*)(Qx + tq * D + h * 256 + 128 * hh + 32 * k4 + 8 * fq);
; #pragma unroll
;                 for (int k8 = 0; k8 < 4; ++k8) { bf16x8 av[4];
; #pragma unroll
;                     for (int kt = 0; kt < 4; ++kt) av[kt] = *(const LAS bf16x8*)(KL + (16 * (4 * k8 + kt) + fr) * KSTR + (32 * k4 + 8 * fq) * 2);
.Lxa_prio:
	s_mov_b32 s48, 0x3d800000
	v_and_b32_e32 v236, 63, v67
	v_and_b32_e32 v237, 15, v236
	v_lshrrev_b32_e32 v248, 4, v236
	v_xor_b32_e32 v234, 16, v236
	v_lshlrev_b32_e32 v234, 2, v234
	v_xor_b32_e32 v235, 32, v236
	v_lshlrev_b32_e32 v235, 2, v235
	v_add_u32_e32 v249, 0, v248
	v_xor_b32_e32 v198, v237, v249
	v_lshl_add_u32 v249, s16, 5, v249
	v_lshlrev_b32_e32 v249, 11, v249
	v_lshl_add_u32 v198, v198, 4, v249
	v_add_u32_e32 v249, 4, v248
	v_xor_b32_e32 v199, v237, v249
	v_lshl_add_u32 v249, s16, 5, v249
	v_lshlrev_b32_e32 v249, 11, v249
	v_lshl_add_u32 v199, v199, 4, v249
	v_add_u32_e32 v249, 8, v248
	v_xor_b32_e32 v200, v237, v249
	v_lshl_add_u32 v249, s16, 5, v249
	v_lshlrev_b32_e32 v249, 11, v249
	v_lshl_add_u32 v200, v200, 4, v249
	v_add_u32_e32 v249, 12, v248
	v_xor_b32_e32 v201, v237, v249
	v_lshl_add_u32 v249, s16, 5, v249
	v_lshlrev_b32_e32 v249, 11, v249
	v_lshl_add_u32 v201, v201, 4, v249
	v_add_u32_e32 v249, 0, v248
	v_xor_b32_e32 v249, v249, v237
	v_lshlrev_b32_e32 v249, 4, v249
	v_lshl_add_u32 v206, v237, 8, v249
	v_add_u32_e32 v212, 0x10000, v206
	v_add_u32_e32 v249, 4, v248
	v_xor_b32_e32 v249, v249, v237
	v_lshlrev_b32_e32 v249, 4, v249
	v_lshl_add_u32 v207, v237, 8, v249
	v_add_u32_e32 v213, 0x10000, v207
	v_add_u32_e32 v249, 8, v248
	v_xor_b32_e32 v249, v249, v237
	v_lshlrev_b32_e32 v249, 4, v249
	v_lshl_add_u32 v208, v237, 8, v249
	v_add_u32_e32 v214, 0x10000, v208
	v_add_u32_e32 v249, 12, v248
	v_xor_b32_e32 v249, v249, v237
	v_lshlrev_b32_e32 v249, 4, v249
	v_lshl_add_u32 v209, v237, 8, v249
	v_add_u32_e32 v215, 0x10000, v209
	v_lshrrev_b32_e32 v0, 1, v248
	v_add_u32_e32 v249, 0, v0
	v_xor_b32_e32 v249, v249, v237
	v_lshlrev_b32_e32 v249, 4, v249
	v_lshl_add_u32 v216, v237, 9, v249
	v_add_u32_e32 v249, 2, v0
	v_xor_b32_e32 v249, v249, v237
	v_lshlrev_b32_e32 v249, 4, v249
	v_lshl_add_u32 v217, v237, 9, v249
	v_add_u32_e32 v249, 4, v0
	v_xor_b32_e32 v249, v249, v237
	v_lshlrev_b32_e32 v249, 4, v249
	v_lshl_add_u32 v218, v237, 9, v249
	v_add_u32_e32 v249, 6, v0
	v_xor_b32_e32 v249, v249, v237
	v_lshlrev_b32_e32 v249, 4, v249
	v_lshl_add_u32 v219, v237, 9, v249
	v_add_u32_e32 v249, 8, v0
	v_xor_b32_e32 v249, v249, v237
	v_lshlrev_b32_e32 v249, 4, v249
	v_lshl_add_u32 v220, v237, 9, v249
	v_add_u32_e32 v249, 10, v0
	v_xor_b32_e32 v249, v249, v237
	v_lshlrev_b32_e32 v249, 4, v249
	v_lshl_add_u32 v221, v237, 9, v249
	v_add_u32_e32 v249, 12, v0
	v_xor_b32_e32 v249, v249, v237
	v_lshlrev_b32_e32 v249, 4, v249
	v_lshl_add_u32 v222, v237, 9, v249
	v_add_u32_e32 v249, 14, v0
	v_xor_b32_e32 v249, v249, v237
	v_lshlrev_b32_e32 v249, 4, v249
	v_lshl_add_u32 v223, v237, 9, v249
	v_and_b32_e32 v249, 1, v248
	v_lshlrev_b32_e32 v249, 3, v249
	v_add_u32_e32 v216, v216, v249
	v_add_u32_e32 v224, 0x10000, v216
	v_add_u32_e32 v217, v217, v249
	v_add_u32_e32 v225, 0x10000, v217
	v_add_u32_e32 v218, v218, v249
	v_add_u32_e32 v226, 0x10000, v218
	v_add_u32_e32 v219, v219, v249
	v_add_u32_e32 v227, 0x10000, v219
	v_add_u32_e32 v220, v220, v249
	v_add_u32_e32 v228, 0x10000, v220
	v_add_u32_e32 v221, v221, v249
	v_add_u32_e32 v229, 0x10000, v221
	v_add_u32_e32 v222, v222, v249
	v_add_u32_e32 v230, 0x10000, v222
	v_add_u32_e32 v223, v223, v249
	v_add_u32_e32 v231, 0x10000, v223
	v_lshl_add_u32 v249, s16, 4, v237
	v_lshlrev_b32_e32 v249, 11, v249
	v_lshl_add_u32 v232, v248, 4, v249
	v_lshl_add_u32 v233, v248, 3, v249
	v_readlane_b32 s44, v252, 0
	s_nop 3
	s_and_b32 s45, s44, 7
	s_lshr_b32 s46, s44, 3
	s_and_b32 s47, s45, 1
	s_lshl_b32 s47, s47, 4
	s_and_b32 s17, s46, 15
	s_or_b32 s17, s17, s47
	s_lshr_b32 s47, s46, 4
	s_lshl_b32 s47, s47, 6
	s_or_b32 s17, s17, s47
	s_lshr_b32 s47, s45, 1
	s_lshl_b32 s47, s47, 7
	s_or_b32 s17, s17, s47
	s_and_b32 s44, s17, 31
	s_bfe_u32 s45, s17, 0x20005
	s_lshr_b32 s46, s17, 7
	s_lshl_b32 s47, s46, 12
	s_lshl_b32 s44, s44, 7
	s_add_u32 s47, s47, s44
	s_lshl_b32 s47, s47, 11
	s_lshl_b32 s44, s45, 9
	s_add_u32 s47, s47, s44
	s_add_u32 s20, s0, s47
	s_addc_u32 s21, s1, 0
	s_add_u32 s22, s38, s47
	s_addc_u32 s23, s39, 0
	s_lshl_b32 s47, s46, 19
	s_add_u32 s47, s47, s44
	s_add_u32 s24, s36, s47
	s_addc_u32 s25, s37, 0
	s_lshl_b32 s47, s45, 19
	s_lshl_b32 s44, s46, 9
	s_add_u32 s47, s47, s44
	s_add_u32 s42, s2, s47
	s_addc_u32 s43, s3, 0
	s_add_u32 s44, s24, 0
	s_addc_u32 s45, s25, 0
	s_add_u32 s46, s44, 0x8000
	s_addc_u32 s47, s45, 0
	s_add_u32 m0, s49, 0
	s_nop 0
	global_load_lds_dwordx4 v198, s[44:45]
	s_add_u32 m0, s49, 1024
	s_nop 0
	global_load_lds_dwordx4 v199, s[44:45]
	s_add_u32 m0, s49, 2048
	s_nop 0
	global_load_lds_dwordx4 v200, s[44:45]
	s_add_u32 m0, s49, 3072
	s_nop 0
	global_load_lds_dwordx4 v201, s[44:45]
	s_add_u32 m0, s49, 4096
	s_nop 0
	global_load_lds_dwordx4 v198, s[46:47]
	s_add_u32 m0, s49, 5120
	s_nop 0
	global_load_lds_dwordx4 v199, s[46:47]
	s_add_u32 m0, s49, 6144
	s_nop 0
	global_load_lds_dwordx4 v200, s[46:47]
	s_add_u32 m0, s49, 7168
	s_nop 0
	global_load_lds_dwordx4 v201, s[46:47]
	global_load_dwordx4 v[66:69], v232, s[20:21]
	global_load_dwordx4 v[70:73], v232, s[20:21] offset:64
	global_load_dwordx4 v[74:77], v232, s[20:21] offset:128
	global_load_dwordx4 v[78:81], v232, s[20:21] offset:192
	global_load_dwordx4 v[82:85], v232, s[20:21] offset:256
	global_load_dwordx4 v[86:89], v232, s[20:21] offset:320
	global_load_dwordx4 v[90:93], v232, s[20:21] offset:384
	global_load_dwordx4 v[94:97], v232, s[20:21] offset:448
	s_waitcnt vmcnt(0)
	s_barrier
; #define LAS __attribute__((address_space(3)))
; #define MFMA16(a, b, c) __builtin_amdgcn_mfma_f32_16x16x32_bf16((a), (b), (c), 0, 0, 0)
; #define DSEC(k) do { if (PROBE_DSEC) { const unsigned long long tn_ = __builtin_amdgcn_s_memrealtime(); if (PROBE_DSEC == (k)) tsec += tn_ - tl_; tl_ = tn_; } } while (0)
; #define XK_LOAD(R, b_, h_, hh_) do { _Pragma("unroll") for (int i = 0; i < 8; ++i) { const int p = tid + 512 * i, m = p >> 4, cb = p & 15; R[i] = *(const u32x4*)(memK + (size_t)((b_) * NMEM + m) * D + (h_) * 256 + 128 * (hh_) + 8 * cb); } } while (0)
; #define XK_WRITE(R) do { _Pragma("unroll") for (int i = 0; i < 8; ++i) { const int p = tid + 512 * i, m = p >> 4, cb = p & 15; *(LAS u32x4*)(KL + m * KSTR + 16 * cb) = R[i]; } } while (0)
; #define XV_LOAD(R, b_, h_, hh_) do { _Pragma("unroll") for (int i = 0; i < 8; ++i) { const int p = tid + 512 * i, dhr = p >> 5, c = p & 31; R[i] = *(const u32x4*)(memVT + (size_t)((h_) * 256 + 128 * (hh_) + dhr) * MROWS + (b_) * NMEM + 8 * c); } } while (0)
; #define XV_WRITE(R) do { _Pragma("unroll") for (int i = 0; i < 8; ++i) { const int p = tid + 512 * i, dhr = p >> 5, c = p & 31; u32x2 lo, hi; lo.x = R[i].x; lo.y = R[i].y; hi.x = R[i].z; hi.y = R[i].w; \
;         *(LAS u32x2*)(VL + vt_off(dhr, 2 * c)) = lo; *(LAS u32x2*)(VL + vt_off(dhr, 2 * c + 1)) = hi; } } while (0)
; DI void xattn_phase(LAS unsigned char* L, const bf16* Qx, const bf16* memK, const bf16* memVT, bf16* Ox, int G, int bid, int tid, unsigned long long& tsec) {
;     ...
;         for (int hh = 0; hh < 2; ++hh) {
;             __syncthreads();
;             XK_WRITE(ra);
;             if (hh == 0) { XV_WRITE(rb); XK_LOAD(ra, b, h, 1); XV_LOAD(rb, b, h, 1); }
;             else XK_LOAD(ra, bn, hn, 0);
;             __syncthreads();
;             DSEC(11);
; #pragma unroll
;             for (int k4 = 0; k4 < 4; ++k4) { const bf16x8 qk = *(const bf16x8*)(Qx + tq * D + h * 256 + 128 * hh + 32 * k4 + 8 * fq);
; #pragma unroll
;                 for (int k8 = 0; k8 < 4; ++k8) { bf16x8 av[4];
; #pragma unroll
;                     for (int kt = 0; kt < 4; ++kt) av[kt] = *(const LAS bf16x8*)(KL + (16 * (4 * k8 + kt) + fr) * KSTR + (32 * k4 + 8 * fq) * 2);
; #pragma unroll
;                     for (int kt = 0; kt < 4; ++kt) s[4 * k8 + kt] = MFMA16(av[kt], qk, s[4 * k8 + kt]); } }
.Lxa_loop:
	s_add_u32 s44, s24, 256
	s_addc_u32 s45, s25, 0
	s_add_u32 s46, s44, 0x8000
	s_addc_u32 s47, s45, 0
	s_add_u32 m0, s49, 65536
	s_nop 0
	global_load_lds_dwordx4 v198, s[44:45]
	s_add_u32 m0, s49, 66560
	s_nop 0
	global_load_lds_dwordx4 v199, s[44:45]
	s_add_u32 m0, s49, 67584
	s_nop 0
	global_load_lds_dwordx4 v200, s[44:45]
	s_add_u32 m0, s49, 68608
	s_nop 0
	global_load_lds_dwordx4 v201, s[44:45]
	s_add_u32 m0, s49, 69632
	s_nop 0
	global_load_lds_dwordx4 v198, s[46:47]
	s_add_u32 m0, s49, 70656
	s_nop 0
	global_load_lds_dwordx4 v199, s[46:47]
	s_add_u32 m0, s49, 71680
	s_nop 0
	global_load_lds_dwordx4 v200, s[46:47]
	s_add_u32 m0, s49, 72704
	s_nop 0
	global_load_lds_dwordx4 v201, s[46:47]
	ds_read_b128 v[98:101], v206 offset:0
	ds_read_b128 v[102:105], v206 offset:4096
	ds_read_b128 v[106:109], v206 offset:8192
	ds_read_b128 v[110:113], v206 offset:12288
	ds_read_b128 v[114:117], v206 offset:16384
	ds_read_b128 v[118:121], v206 offset:20480
	ds_read_b128 v[122:125], v206 offset:24576
	ds_read_b128 v[126:129], v206 offset:28672
	ds_read_b128 v[130:133], v206 offset:32768
	ds_read_b128 v[134:137], v206 offset:36864
	ds_read_b128 v[138:141], v206 offset:40960
	ds_read_b128 v[142:145], v206 offset:45056
	ds_read_b128 v[146:149], v206 offset:49152
	ds_read_b128 v[150:153], v206 offset:53248
	ds_read_b128 v[154:157], v206 offset:57344
	ds_read_b128 v[158:161], v206 offset:61440
	s_waitcnt lgkmcnt(8)
	v_mfma_f32_16x16x32_bf16 v[2:5], v[98:101], v[66:69], 0
	ds_read_b128 v[98:101], v207 offset:0
	v_mfma_f32_16x16x32_bf16 v[6:9], v[102:105], v[66:69], 0
	ds_read_b128 v[102:105], v207 offset:4096
	v_mfma_f32_16x16x32_bf16 v[10:13], v[106:109], v[66:69], 0
	ds_read_b128 v[106:109], v207 offset:8192
	v_mfma_f32_16x16x32_bf16 v[14:17], v[110:113], v[66:69], 0
	ds_read_b128 v[110:113], v207 offset:12288
	v_mfma_f32_16x16x32_bf16 v[18:21], v[114:117], v[66:69], 0
	ds_read_b128 v[114:117], v207 offset:16384
	v_mfma_f32_16x16x32_bf16 v[22:25], v[118:121], v[66:69], 0
	ds_read_b128 v[118:121], v207 offset:20480
	v_mfma_f32_16x16x32_bf16 v[26:29], v[122:125], v[66:69], 0
	ds_read_b128 v[122:125], v207 offset:24576
	v_mfma_f32_16x16x32_bf16 v[30:33], v[126:129], v[66:69], 0
	ds_read_b128 v[126:129], v207 offset:28672
	s_waitcnt lgkmcnt(8)
	v_mfma_f32_16x16x32_bf16 v[34:37], v[130:133], v[66:69], 0
	ds_read_b128 v[130:133], v207 offset:32768
	v_mfma_f32_16x16x32_bf16 v[38:41], v[134:137], v[66:69], 0
	ds_read_b128 v[134:137], v207 offset:36864
	v_mfma_f32_16x16x32_bf16 v[42:45], v[138:141], v[66:69], 0
	ds_read_b128 v[138:141], v207 offset:40960
	v_mfma_f32_16x16x32_bf16 v[46:49], v[142:145], v[66:69], 0
	ds_read_b128 v[142:145], v207 offset:45056
	v_mfma_f32_16x16x32_bf16 v[50:53], v[146:149], v[66:69], 0
	ds_read_b128 v[146:149], v207 offset:49152
	v_mfma_f32_16x16x32_bf16 v[54:57], v[150:153], v[66:69], 0
	ds_read_b128 v[150:153], v207 offset:53248
	v_mfma_f32_16x16x32_bf16 v[58:61], v[154:157], v[66:69], 0
	ds_read_b128 v[154:157], v207 offset:57344
	v_mfma_f32_16x16x32_bf16 v[62:65], v[158:161], v[66:69], 0
	ds_read_b128 v[158:161], v207 offset:61440
	s_waitcnt lgkmcnt(8)
	v_mfma_f32_16x16x32_bf16 v[2:5], v[98:101], v[70:73], v[2:5]
	ds_read_b128 v[98:101], v208 offset:0
	v_mfma_f32_16x16x32_bf16 v[6:9], v[102:105], v[70:73], v[6:9]
	ds_read_b128 v[102:105], v208 offset:4096
	v_mfma_f32_16x16x32_bf16 v[10:13], v[106:109], v[70:73], v[10:13]
	ds_read_b128 v[106:109], v208 offset:8192
	v_mfma_f32_16x16x32_bf16 v[14:17], v[110:113], v[70:73], v[14:17]
	ds_read_b128 v[110:113], v208 offset:12288
	v_mfma_f32_16x16x32_bf16 v[18:21], v[114:117], v[70:73], v[18:21]
	ds_read_b128 v[114:117], v208 offset:16384
	v_mfma_f32_16x16x32_bf16 v[22:25], v[118:121], v[70:73], v[22:25]
	ds_read_b128 v[118:121], v208 offset:20480
	v_mfma_f32_16x16x32_bf16 v[26:29], v[122:125], v[70:73], v[26:29]
	ds_read_b128 v[122:125], v208 offset:24576
	v_mfma_f32_16x16x32_bf16 v[30:33], v[126:129], v[70:73], v[30:33]
	ds_read_b128 v[126:129], v208 offset:28672
	s_waitcnt lgkmcnt(8)
	v_mfma_f32_16x16x32_bf16 v[34:37], v[130:133], v[70:73], v[34:37]
	ds_read_b128 v[130:133], v208 offset:32768
	v_mfma_f32_16x16x32_bf16 v[38:41], v[134:137], v[70:73], v[38:41]
	ds_read_b128 v[134:137], v208 offset:36864
	v_mfma_f32_16x16x32_bf16 v[42:45], v[138:141], v[70:73], v[42:45]
	ds_read_b128 v[138:141], v208 offset:40960
	v_mfma_f32_16x16x32_bf16 v[46:49], v[142:145], v[70:73], v[46:49]
	ds_read_b128 v[142:145], v208 offset:45056
	v_mfma_f32_16x16x32_bf16 v[50:53], v[146:149], v[70:73], v[50:53]
	ds_read_b128 v[146:149], v208 offset:49152
	v_mfma_f32_16x16x32_bf16 v[54:57], v[150:153], v[70:73], v[54:57]
	ds_read_b128 v[150:153], v208 offset:53248
	v_mfma_f32_16x16x32_bf16 v[58:61], v[154:157], v[70:73], v[58:61]
	ds_read_b128 v[154:157], v208 offset:57344
	v_mfma_f32_16x16x32_bf16 v[62:65], v[158:161], v[70:73], v[62:65]
	ds_read_b128 v[158:161], v208 offset:61440
	s_waitcnt lgkmcnt(8)
	v_mfma_f32_16x16x32_bf16 v[2:5], v[98:101], v[74:77], v[2:5]
	ds_read_b128 v[98:101], v209 offset:0
	v_mfma_f32_16x16x32_bf16 v[6:9], v[102:105], v[74:77], v[6:9]
	ds_read_b128 v[102:105], v209 offset:4096
	v_mfma_f32_16x16x32_bf16 v[10:13], v[106:109], v[74:77], v[10:13]
	ds_read_b128 v[106:109], v209 offset:8192
	v_mfma_f32_16x16x32_bf16 v[14:17], v[110:113], v[74:77], v[14:17]
	ds_read_b128 v[110:113], v209 offset:12288
	v_mfma_f32_16x16x32_bf16 v[18:21], v[114:117], v[74:77], v[18:21]
	ds_read_b128 v[114:117], v209 offset:16384
	v_mfma_f32_16x16x32_bf16 v[22:25], v[118:121], v[74:77], v[22:25]
	ds_read_b128 v[118:121], v209 offset:20480
	v_mfma_f32_16x16x32_bf16 v[26:29], v[122:125], v[74:77], v[26:29]
	ds_read_b128 v[122:125], v209 offset:24576
	v_mfma_f32_16x16x32_bf16 v[30:33], v[126:129], v[74:77], v[30:33]
	ds_read_b128 v[126:129], v209 offset:28672
	s_waitcnt lgkmcnt(8)
; #define LAS __attribute__((address_space(3)))
; #define MFMA16(a, b, c) __builtin_amdgcn_mfma_f32_16x16x32_bf16((a), (b), (c), 0, 0, 0)
; #define DSEC(k) do { if (PROBE_DSEC) { const unsigned long long tn_ = __builtin_amdgcn_s_memrealtime(); if (PROBE_DSEC == (k)) tsec += tn_ - tl_; tl_ = tn_; } } while (0)
; #define XK_LOAD(R, b_, h_, hh_) do { _Pragma("unroll") for (int i = 0; i < 8; ++i) { const int p = tid + 512 * i, m = p >> 4, cb = p & 15; R[i] = *(const u32x4*)(memK + (size_t)((b_) * NMEM + m) * D + (h_) * 256 + 128 * (hh_) + 8 * cb); } } while (0)
; #define XK_WRITE(R) do { _Pragma("unroll") for (int i = 0; i < 8; ++i) { const int p = tid + 512 * i, m = p >> 4, cb = p & 15; *(LAS u32x4*)(KL + m * KSTR + 16 * cb) = R[i]; } } while (0)
; #define XV_LOAD(R, b_, h_, hh_) do { _Pragma("unroll") for (int i = 0; i < 8; ++i) { const int p = tid + 512 * i, dhr = p >> 5, c = p & 31; R[i] = *(const u32x4*)(memVT + (size_t)((h_) * 256 + 128 * (hh_) + dhr) * MROWS + (b_) * NMEM + 8 * c); } } while (0)
; #define XV_WRITE(R) do { _Pragma("unroll") for (int i = 0; i < 8; ++i) { const int p = tid + 512 * i, dhr = p >> 5, c = p & 31; u32x2 lo, hi; lo.x = R[i].x; lo.y = R[i].y; hi.x = R[i].z; hi.y = R[i].w; \
;         *(LAS u32x2*)(VL + vt_off(dhr, 2 * c)) = lo; *(LAS u32x2*)(VL + vt_off(dhr, 2 * c + 1)) = hi; } } while (0)
; DI void xattn_phase(LAS unsigned char* L, const bf16* Qx, const bf16* memK, const bf16* memVT, bf16* Ox, int G, int bid, int tid, unsigned long long& tsec) {
;     ...
;         for (int hh = 0; hh < 2; ++hh) {
;             __syncthreads();
;             XK_WRITE(ra);
;             if (hh == 0) { XV_WRITE(rb); XK_LOAD(ra, b, h, 1); XV_LOAD(rb, b, h, 1); }
;             else XK_LOAD(ra, bn, hn, 0);
;             __syncthreads();
;             DSEC(11);
; #pragma unroll
;             for (int k4 = 0; k4 < 4; ++k4) { const bf16x8 qk = *(const bf16x8*)(Qx + tq * D + h * 256 + 128 * hh + 32 * k4 + 8 * fq);
; #pragma unroll
;                 for (int k8 = 0; k8 < 4; ++k8) { bf16x8 av[4];
; #pragma unroll
;                     for (int kt = 0; kt < 4; ++kt) av[kt] = *(const LAS bf16x8*)(KL + (16 * (4 * k8 + kt) + fr) * KSTR + (32 * k4 + 8 * fq) * 2);
; #pragma unroll
;                     for (int kt = 0; kt < 4; ++kt) s[4 * k8 + kt] = MFMA16(av[kt], qk, s[4 * k8 + kt]); } }
	v_mfma_f32_16x16x32_bf16 v[34:37], v[130:133], v[74:77], v[34:37]
	ds_read_b128 v[130:133], v209 offset:32768
	v_mfma_f32_16x16x32_bf16 v[38:41], v[134:137], v[74:77], v[38:41]
	ds_read_b128 v[134:137], v209 offset:36864
	v_mfma_f32_16x16x32_bf16 v[42:45], v[138:141], v[74:77], v[42:45]
	ds_read_b128 v[138:141], v209 offset:40960
	v_mfma_f32_16x16x32_bf16 v[46:49], v[142:145], v[74:77], v[46:49]
	ds_read_b128 v[142:145], v209 offset:45056
	v_mfma_f32_16x16x32_bf16 v[50:53], v[146:149], v[74:77], v[50:53]
	ds_read_b128 v[146:149], v209 offset:49152
	v_mfma_f32_16x16x32_bf16 v[54:57], v[150:153], v[74:77], v[54:57]
	ds_read_b128 v[150:153], v209 offset:53248
	v_mfma_f32_16x16x32_bf16 v[58:61], v[154:157], v[74:77], v[58:61]
	ds_read_b128 v[154:157], v209 offset:57344
	v_mfma_f32_16x16x32_bf16 v[62:65], v[158:161], v[74:77], v[62:65]
	ds_read_b128 v[158:161], v209 offset:61440
	s_waitcnt lgkmcnt(8)
	v_mfma_f32_16x16x32_bf16 v[2:5], v[98:101], v[78:81], v[2:5]
	v_mfma_f32_16x16x32_bf16 v[6:9], v[102:105], v[78:81], v[6:9]
	v_mfma_f32_16x16x32_bf16 v[10:13], v[106:109], v[78:81], v[10:13]
	v_mfma_f32_16x16x32_bf16 v[14:17], v[110:113], v[78:81], v[14:17]
	v_mfma_f32_16x16x32_bf16 v[18:21], v[114:117], v[78:81], v[18:21]
	v_mfma_f32_16x16x32_bf16 v[22:25], v[118:121], v[78:81], v[22:25]
	v_mfma_f32_16x16x32_bf16 v[26:29], v[122:125], v[78:81], v[26:29]
	v_mfma_f32_16x16x32_bf16 v[30:33], v[126:129], v[78:81], v[30:33]
	s_waitcnt lgkmcnt(0)
	v_mfma_f32_16x16x32_bf16 v[34:37], v[130:133], v[78:81], v[34:37]
	v_mfma_f32_16x16x32_bf16 v[38:41], v[134:137], v[78:81], v[38:41]
	v_mfma_f32_16x16x32_bf16 v[42:45], v[138:141], v[78:81], v[42:45]
	v_mfma_f32_16x16x32_bf16 v[46:49], v[142:145], v[78:81], v[46:49]
	v_mfma_f32_16x16x32_bf16 v[50:53], v[146:149], v[78:81], v[50:53]
	v_mfma_f32_16x16x32_bf16 v[54:57], v[150:153], v[78:81], v[54:57]
	v_mfma_f32_16x16x32_bf16 v[58:61], v[154:157], v[78:81], v[58:61]
	v_mfma_f32_16x16x32_bf16 v[62:65], v[158:161], v[78:81], v[62:65]
	s_waitcnt vmcnt(0)
	s_barrier
	s_add_u32 s44, s42, 0
	s_addc_u32 s45, s43, 0
	v_lshrrev_b32_e32 v237, 5, v236
	v_add_u32_e32 v237, 0, v237
	v_and_b32_e32 v248, 31, v236
	v_xor_b32_e32 v248, v248, v237
	v_lshl_add_u32 v237, s16, 4, v237
	v_lshlrev_b32_e32 v237, 11, v237
	v_lshl_add_u32 v237, v248, 4, v237
	s_add_u32 m0, s49, 0
	s_nop 0
	global_load_lds_dwordx4 v237, s[44:45]
	v_lshrrev_b32_e32 v237, 5, v236
	v_add_u32_e32 v237, 2, v237
	v_and_b32_e32 v248, 31, v236
	v_xor_b32_e32 v248, v248, v237
	v_lshl_add_u32 v237, s16, 4, v237
	v_lshlrev_b32_e32 v237, 11, v237
	v_lshl_add_u32 v237, v248, 4, v237
	s_add_u32 m0, s49, 1024
	s_nop 0
	global_load_lds_dwordx4 v237, s[44:45]
	v_lshrrev_b32_e32 v237, 5, v236
	v_add_u32_e32 v237, 4, v237
	v_and_b32_e32 v248, 31, v236
	v_xor_b32_e32 v248, v248, v237
	v_lshl_add_u32 v237, s16, 4, v237
	v_lshlrev_b32_e32 v237, 11, v237
	v_lshl_add_u32 v237, v248, 4, v237
	s_add_u32 m0, s49, 2048
	s_nop 0
	global_load_lds_dwordx4 v237, s[44:45]
	v_lshrrev_b32_e32 v237, 5, v236
	v_add_u32_e32 v237, 6, v237
	v_and_b32_e32 v248, 31, v236
	v_xor_b32_e32 v248, v248, v237
	v_lshl_add_u32 v237, s16, 4, v237
	v_lshlrev_b32_e32 v237, 11, v237
	v_lshl_add_u32 v237, v248, 4, v237
	s_add_u32 m0, s49, 3072
	s_nop 0
	global_load_lds_dwordx4 v237, s[44:45]
	v_lshrrev_b32_e32 v237, 5, v236
	v_add_u32_e32 v237, 8, v237
	v_and_b32_e32 v248, 31, v236
	v_xor_b32_e32 v248, v248, v237
	v_lshl_add_u32 v237, s16, 4, v237
	v_lshlrev_b32_e32 v237, 11, v237
	v_lshl_add_u32 v237, v248, 4, v237
	s_add_u32 m0, s49, 4096
	s_nop 0
	global_load_lds_dwordx4 v237, s[44:45]
	v_lshrrev_b32_e32 v237, 5, v236
	v_add_u32_e32 v237, 10, v237
	v_and_b32_e32 v248, 31, v236
	v_xor_b32_e32 v248, v248, v237
	v_lshl_add_u32 v237, s16, 4, v237
	v_lshlrev_b32_e32 v237, 11, v237
	v_lshl_add_u32 v237, v248, 4, v237
	s_add_u32 m0, s49, 5120
	s_nop 0
	global_load_lds_dwordx4 v237, s[44:45]
	v_lshrrev_b32_e32 v237, 5, v236
	v_add_u32_e32 v237, 12, v237
	v_and_b32_e32 v248, 31, v236
	v_xor_b32_e32 v248, v248, v237
	v_lshl_add_u32 v237, s16, 4, v237
	v_lshlrev_b32_e32 v237, 11, v237
	v_lshl_add_u32 v237, v248, 4, v237
	s_add_u32 m0, s49, 6144
	s_nop 0
	global_load_lds_dwordx4 v237, s[44:45]
	v_lshrrev_b32_e32 v237, 5, v236
	v_add_u32_e32 v237, 14, v237
	v_and_b32_e32 v248, 31, v236
	v_xor_b32_e32 v248, v248, v237
	v_lshl_add_u32 v237, s16, 4, v237
	v_lshlrev_b32_e32 v237, 11, v237
	v_lshl_add_u32 v237, v248, 4, v237
	s_add_u32 m0, s49, 7168
	s_nop 0
	global_load_lds_dwordx4 v237, s[44:45]
	ds_read_b128 v[98:101], v212 offset:0
	ds_read_b128 v[102:105], v212 offset:4096
	ds_read_b128 v[106:109], v212 offset:8192
	ds_read_b128 v[110:113], v212 offset:12288
	ds_read_b128 v[114:117], v212 offset:16384
	ds_read_b128 v[118:121], v212 offset:20480
	ds_read_b128 v[122:125], v212 offset:24576
	ds_read_b128 v[126:129], v212 offset:28672
	ds_read_b128 v[130:133], v212 offset:32768
	ds_read_b128 v[134:137], v212 offset:36864
	ds_read_b128 v[138:141], v212 offset:40960
	ds_read_b128 v[142:145], v212 offset:45056
	ds_read_b128 v[146:149], v212 offset:49152
	ds_read_b128 v[150:153], v212 offset:53248
	ds_read_b128 v[154:157], v212 offset:57344
	ds_read_b128 v[158:161], v212 offset:61440
	s_waitcnt lgkmcnt(8)
; #define LAS __attribute__((address_space(3)))
; #define MFMA16(a, b, c) __builtin_amdgcn_mfma_f32_16x16x32_bf16((a), (b), (c), 0, 0, 0)
; DI void xattn_phase(LAS unsigned char* L, const bf16* Qx, const bf16* memK, const bf16* memVT, bf16* Ox, int G, int bid, int tid, unsigned long long& tsec) {
;     ...
; #pragma unroll
;             for (int k4 = 0; k4 < 4; ++k4) { const bf16x8 qk = *(const bf16x8*)(Qx + tq * D + h * 256 + 128 * hh + 32 * k4 + 8 * fq);
; #pragma unroll
;                 for (int k8 = 0; k8 < 4; ++k8) { bf16x8 av[4];
; #pragma unroll
;                     for (int kt = 0; kt < 4; ++kt) av[kt] = *(const LAS bf16x8*)(KL + (16 * (4 * k8 + kt) + fr) * KSTR + (32 * k4 + 8 * fq) * 2);
; #pragma unroll
;                     for (int kt = 0; kt < 4; ++kt) s[4 * k8 + kt] = MFMA16(av[kt], qk, s[4 * k8 + kt]); } }
	v_mfma_f32_16x16x32_bf16 v[2:5], v[98:101], v[82:85], v[2:5]
	ds_read_b128 v[98:101], v213 offset:0
	v_mfma_f32_16x16x32_bf16 v[6:9], v[102:105], v[82:85], v[6:9]
	ds_read_b128 v[102:105], v213 offset:4096
	v_mfma_f32_16x16x32_bf16 v[10:13], v[106:109], v[82:85], v[10:13]
	ds_read_b128 v[106:109], v213 offset:8192
	v_mfma_f32_16x16x32_bf16 v[14:17], v[110:113], v[82:85], v[14:17]
	ds_read_b128 v[110:113], v213 offset:12288
	v_mfma_f32_16x16x32_bf16 v[18:21], v[114:117], v[82:85], v[18:21]
	ds_read_b128 v[114:117], v213 offset:16384
	v_mfma_f32_16x16x32_bf16 v[22:25], v[118:121], v[82:85], v[22:25]
	ds_read_b128 v[118:121], v213 offset:20480
	v_mfma_f32_16x16x32_bf16 v[26:29], v[122:125], v[82:85], v[26:29]
	ds_read_b128 v[122:125], v213 offset:24576
	v_mfma_f32_16x16x32_bf16 v[30:33], v[126:129], v[82:85], v[30:33]
	ds_read_b128 v[126:129], v213 offset:28672
	s_waitcnt lgkmcnt(8)
	v_mfma_f32_16x16x32_bf16 v[34:37], v[130:133], v[82:85], v[34:37]
	ds_read_b128 v[130:133], v213 offset:32768
	v_mfma_f32_16x16x32_bf16 v[38:41], v[134:137], v[82:85], v[38:41]
	ds_read_b128 v[134:137], v213 offset:36864
	v_mfma_f32_16x16x32_bf16 v[42:45], v[138:141], v[82:85], v[42:45]
	ds_read_b128 v[138:141], v213 offset:40960
	v_mfma_f32_16x16x32_bf16 v[46:49], v[142:145], v[82:85], v[46:49]
	ds_read_b128 v[142:145], v213 offset:45056
	v_mfma_f32_16x16x32_bf16 v[50:53], v[146:149], v[82:85], v[50:53]
	ds_read_b128 v[146:149], v213 offset:49152
	v_mfma_f32_16x16x32_bf16 v[54:57], v[150:153], v[82:85], v[54:57]
	ds_read_b128 v[150:153], v213 offset:53248
	v_mfma_f32_16x16x32_bf16 v[58:61], v[154:157], v[82:85], v[58:61]
	ds_read_b128 v[154:157], v213 offset:57344
	v_mfma_f32_16x16x32_bf16 v[62:65], v[158:161], v[82:85], v[62:65]
	ds_read_b128 v[158:161], v213 offset:61440
	s_waitcnt lgkmcnt(8)
	v_mfma_f32_16x16x32_bf16 v[2:5], v[98:101], v[86:89], v[2:5]
	ds_read_b128 v[98:101], v214 offset:0
	v_mfma_f32_16x16x32_bf16 v[6:9], v[102:105], v[86:89], v[6:9]
	ds_read_b128 v[102:105], v214 offset:4096
	v_mfma_f32_16x16x32_bf16 v[10:13], v[106:109], v[86:89], v[10:13]
	ds_read_b128 v[106:109], v214 offset:8192
	v_mfma_f32_16x16x32_bf16 v[14:17], v[110:113], v[86:89], v[14:17]
	ds_read_b128 v[110:113], v214 offset:12288
	v_mfma_f32_16x16x32_bf16 v[18:21], v[114:117], v[86:89], v[18:21]
	ds_read_b128 v[114:117], v214 offset:16384
	v_mfma_f32_16x16x32_bf16 v[22:25], v[118:121], v[86:89], v[22:25]
	ds_read_b128 v[118:121], v214 offset:20480
	v_mfma_f32_16x16x32_bf16 v[26:29], v[122:125], v[86:89], v[26:29]
	ds_read_b128 v[122:125], v214 offset:24576
	v_mfma_f32_16x16x32_bf16 v[30:33], v[126:129], v[86:89], v[30:33]
	ds_read_b128 v[126:129], v214 offset:28672
	s_waitcnt lgkmcnt(8)
	v_mfma_f32_16x16x32_bf16 v[34:37], v[130:133], v[86:89], v[34:37]
	ds_read_b128 v[130:133], v214 offset:32768
	v_mfma_f32_16x16x32_bf16 v[38:41], v[134:137], v[86:89], v[38:41]
	ds_read_b128 v[134:137], v214 offset:36864
	v_mfma_f32_16x16x32_bf16 v[42:45], v[138:141], v[86:89], v[42:45]
	ds_read_b128 v[138:141], v214 offset:40960
	v_mfma_f32_16x16x32_bf16 v[46:49], v[142:145], v[86:89], v[46:49]
	ds_read_b128 v[142:145], v214 offset:45056
	v_mfma_f32_16x16x32_bf16 v[50:53], v[146:149], v[86:89], v[50:53]
	ds_read_b128 v[146:149], v214 offset:49152
	v_mfma_f32_16x16x32_bf16 v[54:57], v[150:153], v[86:89], v[54:57]
	ds_read_b128 v[150:153], v214 offset:53248
	v_mfma_f32_16x16x32_bf16 v[58:61], v[154:157], v[86:89], v[58:61]
	ds_read_b128 v[154:157], v214 offset:57344
	v_mfma_f32_16x16x32_bf16 v[62:65], v[158:161], v[86:89], v[62:65]
	ds_read_b128 v[158:161], v214 offset:61440
	s_waitcnt lgkmcnt(8)
	v_mfma_f32_16x16x32_bf16 v[2:5], v[98:101], v[90:93], v[2:5]
	ds_read_b128 v[98:101], v215 offset:0
	v_mfma_f32_16x16x32_bf16 v[6:9], v[102:105], v[90:93], v[6:9]
	ds_read_b128 v[102:105], v215 offset:4096
	v_mfma_f32_16x16x32_bf16 v[10:13], v[106:109], v[90:93], v[10:13]
	ds_read_b128 v[106:109], v215 offset:8192
	v_mfma_f32_16x16x32_bf16 v[14:17], v[110:113], v[90:93], v[14:17]
	ds_read_b128 v[110:113], v215 offset:12288
	v_mfma_f32_16x16x32_bf16 v[18:21], v[114:117], v[90:93], v[18:21]
	ds_read_b128 v[114:117], v215 offset:16384
	v_mfma_f32_16x16x32_bf16 v[22:25], v[118:121], v[90:93], v[22:25]
	ds_read_b128 v[118:121], v215 offset:20480
	v_mfma_f32_16x16x32_bf16 v[26:29], v[122:125], v[90:93], v[26:29]
	ds_read_b128 v[122:125], v215 offset:24576
	v_mfma_f32_16x16x32_bf16 v[30:33], v[126:129], v[90:93], v[30:33]
	ds_read_b128 v[126:129], v215 offset:28672
	s_waitcnt lgkmcnt(8)
	v_mfma_f32_16x16x32_bf16 v[34:37], v[130:133], v[90:93], v[34:37]
	ds_read_b128 v[130:133], v215 offset:32768
	v_mfma_f32_16x16x32_bf16 v[38:41], v[134:137], v[90:93], v[38:41]
	ds_read_b128 v[134:137], v215 offset:36864
	v_mfma_f32_16x16x32_bf16 v[42:45], v[138:141], v[90:93], v[42:45]
	ds_read_b128 v[138:141], v215 offset:40960
	v_mfma_f32_16x16x32_bf16 v[46:49], v[142:145], v[90:93], v[46:49]
	ds_read_b128 v[142:145], v215 offset:45056
	v_mfma_f32_16x16x32_bf16 v[50:53], v[146:149], v[90:93], v[50:53]
	ds_read_b128 v[146:149], v215 offset:49152
	v_mfma_f32_16x16x32_bf16 v[54:57], v[150:153], v[90:93], v[54:57]
	ds_read_b128 v[150:153], v215 offset:53248
	v_mfma_f32_16x16x32_bf16 v[58:61], v[154:157], v[90:93], v[58:61]
	ds_read_b128 v[154:157], v215 offset:57344
	v_mfma_f32_16x16x32_bf16 v[62:65], v[158:161], v[90:93], v[62:65]
	ds_read_b128 v[158:161], v215 offset:61440
	s_waitcnt lgkmcnt(8)
; #define LAS __attribute__((address_space(3)))
; #define MFMA16(a, b, c) __builtin_amdgcn_mfma_f32_16x16x32_bf16((a), (b), (c), 0, 0, 0)
; #define DSEC(k) do { if (PROBE_DSEC) { const unsigned long long tn_ = __builtin_amdgcn_s_memrealtime(); if (PROBE_DSEC == (k)) tsec += tn_ - tl_; tl_ = tn_; } } while (0)
; DI void xattn_phase(LAS unsigned char* L, const bf16* Qx, const bf16* memK, const bf16* memVT, bf16* Ox, int G, int bid, int tid, unsigned long long& tsec) {
;     ...
;                     for (int kt = 0; kt < 4; ++kt) av[kt] = *(const LAS bf16x8*)(KL + (16 * (4 * k8 + kt) + fr) * KSTR + (32 * k4 + 8 * fq) * 2);
; #pragma unroll
;                     for (int kt = 0; kt < 4; ++kt) s[4 * k8 + kt] = MFMA16(av[kt], qk, s[4 * k8 + kt]); } }
;         }
;         DSEC(12);
;         float mx = -INFINITY;
; #pragma unroll
;         for (int kt = 0; kt < 16; ++kt)
; #pragma unroll
;             for (int e = 0; e < 4; ++e) { const float v = s[kt][e] * 0.0625f; s[kt][e] = v; mx = fmaxf(mx, v); }
;         mx = fmaxf(mx, __shfl_xor(mx, 16)); mx = fmaxf(mx, __shfl_xor(mx, 32));
	v_mfma_f32_16x16x32_bf16 v[2:5], v[98:101], v[94:97], v[2:5]
	v_mfma_f32_16x16x32_bf16 v[6:9], v[102:105], v[94:97], v[6:9]
	v_mfma_f32_16x16x32_bf16 v[10:13], v[106:109], v[94:97], v[10:13]
	v_mfma_f32_16x16x32_bf16 v[14:17], v[110:113], v[94:97], v[14:17]
	v_mfma_f32_16x16x32_bf16 v[18:21], v[114:117], v[94:97], v[18:21]
	v_mfma_f32_16x16x32_bf16 v[22:25], v[118:121], v[94:97], v[22:25]
	v_mfma_f32_16x16x32_bf16 v[26:29], v[122:125], v[94:97], v[26:29]
	v_mfma_f32_16x16x32_bf16 v[30:33], v[126:129], v[94:97], v[30:33]
	s_waitcnt lgkmcnt(0)
	v_mfma_f32_16x16x32_bf16 v[34:37], v[130:133], v[94:97], v[34:37]
	v_mfma_f32_16x16x32_bf16 v[38:41], v[134:137], v[94:97], v[38:41]
	v_mfma_f32_16x16x32_bf16 v[42:45], v[138:141], v[94:97], v[42:45]
	v_mfma_f32_16x16x32_bf16 v[46:49], v[142:145], v[94:97], v[46:49]
	v_mfma_f32_16x16x32_bf16 v[50:53], v[146:149], v[94:97], v[50:53]
	v_mfma_f32_16x16x32_bf16 v[54:57], v[150:153], v[94:97], v[54:57]
	v_mfma_f32_16x16x32_bf16 v[58:61], v[154:157], v[94:97], v[58:61]
	v_mfma_f32_16x16x32_bf16 v[62:65], v[158:161], v[94:97], v[62:65]
	v_mul_f32_e32 v237, 0x3d800000, v2
	v_mul_f32_e32 v248, 0x3d800000, v3
	v_max_f32_e32 v249, v237, v248
	v_mul_f32_e32 v237, 0x3d800000, v4
	v_mul_f32_e32 v248, 0x3d800000, v5
	v_max3_f32 v249, v249, v237, v248
	v_mul_f32_e32 v237, 0x3d800000, v6
	v_mul_f32_e32 v248, 0x3d800000, v7
	v_max3_f32 v249, v249, v237, v248
	v_mul_f32_e32 v237, 0x3d800000, v8
	v_mul_f32_e32 v248, 0x3d800000, v9
	v_max3_f32 v249, v249, v237, v248
	v_mul_f32_e32 v237, 0x3d800000, v10
	v_mul_f32_e32 v248, 0x3d800000, v11
	v_max3_f32 v249, v249, v237, v248
	v_mul_f32_e32 v237, 0x3d800000, v12
	v_mul_f32_e32 v248, 0x3d800000, v13
	v_max3_f32 v249, v249, v237, v248
	v_mul_f32_e32 v237, 0x3d800000, v14
	v_mul_f32_e32 v248, 0x3d800000, v15
	v_max3_f32 v249, v249, v237, v248
	v_mul_f32_e32 v237, 0x3d800000, v16
	v_mul_f32_e32 v248, 0x3d800000, v17
	v_max3_f32 v249, v249, v237, v248
	v_mul_f32_e32 v237, 0x3d800000, v18
	v_mul_f32_e32 v248, 0x3d800000, v19
	v_max3_f32 v249, v249, v237, v248
	v_mul_f32_e32 v237, 0x3d800000, v20
	v_mul_f32_e32 v248, 0x3d800000, v21
	v_max3_f32 v249, v249, v237, v248
	v_mul_f32_e32 v237, 0x3d800000, v22
	v_mul_f32_e32 v248, 0x3d800000, v23
	v_max3_f32 v249, v249, v237, v248
	v_mul_f32_e32 v237, 0x3d800000, v24
	v_mul_f32_e32 v248, 0x3d800000, v25
	v_max3_f32 v249, v249, v237, v248
	v_mul_f32_e32 v237, 0x3d800000, v26
	v_mul_f32_e32 v248, 0x3d800000, v27
	v_max3_f32 v249, v249, v237, v248
	v_mul_f32_e32 v237, 0x3d800000, v28
	v_mul_f32_e32 v248, 0x3d800000, v29
	v_max3_f32 v249, v249, v237, v248
	v_mul_f32_e32 v237, 0x3d800000, v30
	v_mul_f32_e32 v248, 0x3d800000, v31
	v_max3_f32 v249, v249, v237, v248
	v_mul_f32_e32 v237, 0x3d800000, v32
	v_mul_f32_e32 v248, 0x3d800000, v33
	v_max3_f32 v249, v249, v237, v248
	v_mul_f32_e32 v237, 0x3d800000, v34
	v_mul_f32_e32 v248, 0x3d800000, v35
	v_max3_f32 v249, v249, v237, v248
	v_mul_f32_e32 v237, 0x3d800000, v36
	v_mul_f32_e32 v248, 0x3d800000, v37
	v_max3_f32 v249, v249, v237, v248
	v_mul_f32_e32 v237, 0x3d800000, v38
	v_mul_f32_e32 v248, 0x3d800000, v39
	v_max3_f32 v249, v249, v237, v248
	v_mul_f32_e32 v237, 0x3d800000, v40
	v_mul_f32_e32 v248, 0x3d800000, v41
	v_max3_f32 v249, v249, v237, v248
	v_mul_f32_e32 v237, 0x3d800000, v42
	v_mul_f32_e32 v248, 0x3d800000, v43
	v_max3_f32 v249, v249, v237, v248
	v_mul_f32_e32 v237, 0x3d800000, v44
	v_mul_f32_e32 v248, 0x3d800000, v45
	v_max3_f32 v249, v249, v237, v248
	v_mul_f32_e32 v237, 0x3d800000, v46
	v_mul_f32_e32 v248, 0x3d800000, v47
	v_max3_f32 v249, v249, v237, v248
	v_mul_f32_e32 v237, 0x3d800000, v48
	v_mul_f32_e32 v248, 0x3d800000, v49
	v_max3_f32 v249, v249, v237, v248
	v_mul_f32_e32 v237, 0x3d800000, v50
	v_mul_f32_e32 v248, 0x3d800000, v51
	v_max3_f32 v249, v249, v237, v248
	v_mul_f32_e32 v237, 0x3d800000, v52
	v_mul_f32_e32 v248, 0x3d800000, v53
	v_max3_f32 v249, v249, v237, v248
	v_mul_f32_e32 v237, 0x3d800000, v54
	v_mul_f32_e32 v248, 0x3d800000, v55
	v_max3_f32 v249, v249, v237, v248
	v_mul_f32_e32 v237, 0x3d800000, v56
	v_mul_f32_e32 v248, 0x3d800000, v57
	v_max3_f32 v249, v249, v237, v248
	v_mul_f32_e32 v237, 0x3d800000, v58
	v_mul_f32_e32 v248, 0x3d800000, v59
	v_max3_f32 v249, v249, v237, v248
	v_mul_f32_e32 v237, 0x3d800000, v60
	v_mul_f32_e32 v248, 0x3d800000, v61
	v_max3_f32 v249, v249, v237, v248
	v_mul_f32_e32 v237, 0x3d800000, v62
	v_mul_f32_e32 v248, 0x3d800000, v63
	v_max3_f32 v249, v249, v237, v248
	v_mul_f32_e32 v237, 0x3d800000, v64
	v_mul_f32_e32 v248, 0x3d800000, v65
	v_max3_f32 v249, v249, v237, v248
	ds_bpermute_b32 v237, v234, v249
	s_waitcnt lgkmcnt(0)
	v_max_f32_e32 v237, v237, v237
	v_max_f32_e32 v249, v249, v237
	ds_bpermute_b32 v237, v235, v249
	s_waitcnt lgkmcnt(0)
; DI void xattn_phase(LAS unsigned char* L, const bf16* Qx, const bf16* memK, const bf16* memVT, bf16* Ox, int G, int bid, int tid, unsigned long long& tsec) {
;     ...
;         mx = fmaxf(mx, __shfl_xor(mx, 16)); mx = fmaxf(mx, __shfl_xor(mx, 32));
;         float den = 0.f;
; #pragma unroll
;         for (int kt = 0; kt < 16; ++kt)
; #pragma unroll
;             for (int e = 0; e < 4; ++e) { const float p = __expf(s[kt][e] - mx); s[kt][e] = p; den += p; }
	v_max_f32_e32 v237, v237, v237
	v_max_f32_e32 v249, v249, v237
	v_fma_f32 v2, v2, s48, -v249
	v_fma_f32 v3, v3, s48, -v249
	v_fma_f32 v4, v4, s48, -v249
	v_fma_f32 v5, v5, s48, -v249
	v_fma_f32 v6, v6, s48, -v249
	v_fma_f32 v7, v7, s48, -v249
	v_fma_f32 v8, v8, s48, -v249
	v_fma_f32 v9, v9, s48, -v249
	v_fma_f32 v10, v10, s48, -v249
	v_fma_f32 v11, v11, s48, -v249
	v_fma_f32 v12, v12, s48, -v249
	v_fma_f32 v13, v13, s48, -v249
	v_fma_f32 v14, v14, s48, -v249
	v_fma_f32 v15, v15, s48, -v249
	v_fma_f32 v16, v16, s48, -v249
	v_fma_f32 v17, v17, s48, -v249
	v_fma_f32 v18, v18, s48, -v249
	v_fma_f32 v19, v19, s48, -v249
	v_fma_f32 v20, v20, s48, -v249
	v_fma_f32 v21, v21, s48, -v249
	v_fma_f32 v22, v22, s48, -v249
	v_fma_f32 v23, v23, s48, -v249
	v_fma_f32 v24, v24, s48, -v249
	v_fma_f32 v25, v25, s48, -v249
	v_fma_f32 v26, v26, s48, -v249
	v_fma_f32 v27, v27, s48, -v249
	v_fma_f32 v28, v28, s48, -v249
	v_fma_f32 v29, v29, s48, -v249
	v_fma_f32 v30, v30, s48, -v249
	v_fma_f32 v31, v31, s48, -v249
	v_fma_f32 v32, v32, s48, -v249
	v_fma_f32 v33, v33, s48, -v249
	v_fma_f32 v34, v34, s48, -v249
	v_fma_f32 v35, v35, s48, -v249
	v_fma_f32 v36, v36, s48, -v249
	v_fma_f32 v37, v37, s48, -v249
	v_fma_f32 v38, v38, s48, -v249
	v_fma_f32 v39, v39, s48, -v249
	v_fma_f32 v40, v40, s48, -v249
	v_fma_f32 v41, v41, s48, -v249
	v_fma_f32 v42, v42, s48, -v249
	v_fma_f32 v43, v43, s48, -v249
	v_fma_f32 v44, v44, s48, -v249
	v_fma_f32 v45, v45, s48, -v249
	v_fma_f32 v46, v46, s48, -v249
	v_fma_f32 v47, v47, s48, -v249
	v_fma_f32 v48, v48, s48, -v249
	v_fma_f32 v49, v49, s48, -v249
	v_fma_f32 v50, v50, s48, -v249
	v_fma_f32 v51, v51, s48, -v249
	v_fma_f32 v52, v52, s48, -v249
	v_fma_f32 v53, v53, s48, -v249
	v_fma_f32 v54, v54, s48, -v249
	v_fma_f32 v55, v55, s48, -v249
	v_fma_f32 v56, v56, s48, -v249
	v_fma_f32 v57, v57, s48, -v249
	v_fma_f32 v58, v58, s48, -v249
	v_fma_f32 v59, v59, s48, -v249
	v_fma_f32 v60, v60, s48, -v249
	v_fma_f32 v61, v61, s48, -v249
	v_fma_f32 v62, v62, s48, -v249
	v_fma_f32 v63, v63, s48, -v249
	v_fma_f32 v64, v64, s48, -v249
	v_fma_f32 v65, v65, s48, -v249
	v_mul_f32_e32 v2, 0x3fb8aa3b, v2
	v_mul_f32_e32 v3, 0x3fb8aa3b, v3
	v_mul_f32_e32 v4, 0x3fb8aa3b, v4
	v_mul_f32_e32 v5, 0x3fb8aa3b, v5
	v_mul_f32_e32 v6, 0x3fb8aa3b, v6
	v_mul_f32_e32 v7, 0x3fb8aa3b, v7
	v_mul_f32_e32 v8, 0x3fb8aa3b, v8
	v_mul_f32_e32 v9, 0x3fb8aa3b, v9
	v_mul_f32_e32 v10, 0x3fb8aa3b, v10
	v_mul_f32_e32 v11, 0x3fb8aa3b, v11
	v_mul_f32_e32 v12, 0x3fb8aa3b, v12
	v_mul_f32_e32 v13, 0x3fb8aa3b, v13
	v_mul_f32_e32 v14, 0x3fb8aa3b, v14
	v_mul_f32_e32 v15, 0x3fb8aa3b, v15
	v_mul_f32_e32 v16, 0x3fb8aa3b, v16
	v_mul_f32_e32 v17, 0x3fb8aa3b, v17
	v_mul_f32_e32 v18, 0x3fb8aa3b, v18
	v_mul_f32_e32 v19, 0x3fb8aa3b, v19
	v_mul_f32_e32 v20, 0x3fb8aa3b, v20
	v_mul_f32_e32 v21, 0x3fb8aa3b, v21
	v_mul_f32_e32 v22, 0x3fb8aa3b, v22
	v_mul_f32_e32 v23, 0x3fb8aa3b, v23
	v_mul_f32_e32 v24, 0x3fb8aa3b, v24
	v_mul_f32_e32 v25, 0x3fb8aa3b, v25
	v_mul_f32_e32 v26, 0x3fb8aa3b, v26
	v_mul_f32_e32 v27, 0x3fb8aa3b, v27
	v_mul_f32_e32 v28, 0x3fb8aa3b, v28
	v_mul_f32_e32 v29, 0x3fb8aa3b, v29
	v_mul_f32_e32 v30, 0x3fb8aa3b, v30
	v_mul_f32_e32 v31, 0x3fb8aa3b, v31
	v_mul_f32_e32 v32, 0x3fb8aa3b, v32
	v_mul_f32_e32 v33, 0x3fb8aa3b, v33
	v_mul_f32_e32 v34, 0x3fb8aa3b, v34
	v_mul_f32_e32 v35, 0x3fb8aa3b, v35
	v_mul_f32_e32 v36, 0x3fb8aa3b, v36
	v_mul_f32_e32 v37, 0x3fb8aa3b, v37
	v_mul_f32_e32 v38, 0x3fb8aa3b, v38
	v_mul_f32_e32 v39, 0x3fb8aa3b, v39
	v_mul_f32_e32 v40, 0x3fb8aa3b, v40
	v_mul_f32_e32 v41, 0x3fb8aa3b, v41
	v_mul_f32_e32 v42, 0x3fb8aa3b, v42
	v_mul_f32_e32 v43, 0x3fb8aa3b, v43
	v_mul_f32_e32 v44, 0x3fb8aa3b, v44
	v_mul_f32_e32 v45, 0x3fb8aa3b, v45
	v_mul_f32_e32 v46, 0x3fb8aa3b, v46
	v_mul_f32_e32 v47, 0x3fb8aa3b, v47
	v_mul_f32_e32 v48, 0x3fb8aa3b, v48
	v_mul_f32_e32 v49, 0x3fb8aa3b, v49
	v_mul_f32_e32 v50, 0x3fb8aa3b, v50
	v_mul_f32_e32 v51, 0x3fb8aa3b, v51
	v_mul_f32_e32 v52, 0x3fb8aa3b, v52
	v_mul_f32_e32 v53, 0x3fb8aa3b, v53
	v_mul_f32_e32 v54, 0x3fb8aa3b, v54
	v_mul_f32_e32 v55, 0x3fb8aa3b, v55
	v_mul_f32_e32 v56, 0x3fb8aa3b, v56
	v_mul_f32_e32 v57, 0x3fb8aa3b, v57
	v_mul_f32_e32 v58, 0x3fb8aa3b, v58
	v_mul_f32_e32 v59, 0x3fb8aa3b, v59
	v_mul_f32_e32 v60, 0x3fb8aa3b, v60
	v_mul_f32_e32 v61, 0x3fb8aa3b, v61
	v_mul_f32_e32 v62, 0x3fb8aa3b, v62
	v_mul_f32_e32 v63, 0x3fb8aa3b, v63
	v_mul_f32_e32 v64, 0x3fb8aa3b, v64
	v_mul_f32_e32 v65, 0x3fb8aa3b, v65
	v_exp_f32_e32 v2, v2
	v_exp_f32_e32 v3, v3
	v_exp_f32_e32 v4, v4
	v_exp_f32_e32 v5, v5
	v_exp_f32_e32 v6, v6
	v_exp_f32_e32 v7, v7
	v_exp_f32_e32 v8, v8
	v_exp_f32_e32 v9, v9
	v_exp_f32_e32 v10, v10
	v_exp_f32_e32 v11, v11
	v_exp_f32_e32 v12, v12
	v_exp_f32_e32 v13, v13
	v_exp_f32_e32 v14, v14
	v_exp_f32_e32 v15, v15
	v_exp_f32_e32 v16, v16
	v_exp_f32_e32 v17, v17
	v_exp_f32_e32 v18, v18
	v_exp_f32_e32 v19, v19
	v_exp_f32_e32 v20, v20
	v_exp_f32_e32 v21, v21
	v_exp_f32_e32 v22, v22
	v_exp_f32_e32 v23, v23
	v_exp_f32_e32 v24, v24
	v_exp_f32_e32 v25, v25
	v_exp_f32_e32 v26, v26
	v_exp_f32_e32 v27, v27
	v_exp_f32_e32 v28, v28
	v_exp_f32_e32 v29, v29
	v_exp_f32_e32 v30, v30
	v_exp_f32_e32 v31, v31
	v_exp_f32_e32 v32, v32
	v_exp_f32_e32 v33, v33
	v_exp_f32_e32 v34, v34
	v_exp_f32_e32 v35, v35
	v_exp_f32_e32 v36, v36
	v_exp_f32_e32 v37, v37
	v_exp_f32_e32 v38, v38
	v_exp_f32_e32 v39, v39
	v_exp_f32_e32 v40, v40
	v_exp_f32_e32 v41, v41
	v_exp_f32_e32 v42, v42
	v_exp_f32_e32 v43, v43
	v_exp_f32_e32 v44, v44
	v_exp_f32_e32 v45, v45
	v_exp_f32_e32 v46, v46
	v_exp_f32_e32 v47, v47
	v_exp_f32_e32 v48, v48
	v_exp_f32_e32 v49, v49
	v_exp_f32_e32 v50, v50
	v_exp_f32_e32 v51, v51
	v_exp_f32_e32 v52, v52
	v_exp_f32_e32 v53, v53
	v_exp_f32_e32 v54, v54
; DI unsigned pk2(float lo, float hi) { const bf2_t r = __builtin_convertvector((f32x2_t){lo, hi}, bf2_t); return __builtin_bit_cast(unsigned, r); }
; #define DSEC(k) do { if (PROBE_DSEC) { const unsigned long long tn_ = __builtin_amdgcn_s_memrealtime(); if (PROBE_DSEC == (k)) tsec += tn_ - tl_; tl_ = tn_; } } while (0)
; #define XV_LOAD(R, b_, h_, hh_) do { _Pragma("unroll") for (int i = 0; i < 8; ++i) { const int p = tid + 512 * i, dhr = p >> 5, c = p & 31; R[i] = *(const u32x4*)(memVT + (size_t)((h_) * 256 + 128 * (hh_) + dhr) * MROWS + (b_) * NMEM + 8 * c); } } while (0)
; #define XV_WRITE(R) do { _Pragma("unroll") for (int i = 0; i < 8; ++i) { const int p = tid + 512 * i, dhr = p >> 5, c = p & 31; u32x2 lo, hi; lo.x = R[i].x; lo.y = R[i].y; hi.x = R[i].z; hi.y = R[i].w; \
;         *(LAS u32x2*)(VL + vt_off(dhr, 2 * c)) = lo; *(LAS u32x2*)(VL + vt_off(dhr, 2 * c + 1)) = hi; } } while (0)
; DI void xattn_phase(LAS unsigned char* L, const bf16* Qx, const bf16* memK, const bf16* memVT, bf16* Ox, int G, int bid, int tid, unsigned long long& tsec) {
;     ...
;             for (int e = 0; e < 4; ++e) { const float p = __expf(s[kt][e] - mx); s[kt][e] = p; den += p; }
;         den += __shfl_xor(den, 16); den += __shfl_xor(den, 32);
;         DSEC(13);
;         bf16x8 pf[8];
; #pragma unroll
;         for (int pp = 0; pp < 8; ++pp) { u32x4 pw; pw.x = pk2(s[2 * pp][0], s[2 * pp][1]); pw.y = pk2(s[2 * pp][2], s[2 * pp][3]); pw.z = pk2(s[2 * pp + 1][0], s[2 * pp + 1][1]); pw.w = pk2(s[2 * pp + 1][2], s[2 * pp + 1][3]); pf[pp] = mk8(pw); }
;         const float inv = __builtin_amdgcn_rcpf(den);
; #pragma unroll
;         for (int hh = 0; hh < 2; ++hh) {
;             if (hh == 1) { DSEC(14); __syncthreads(); XV_WRITE(rb); XV_LOAD(rb, bn, hn, 0); __syncthreads(); DSEC(15); }
	v_exp_f32_e32 v55, v55
	v_exp_f32_e32 v56, v56
	v_exp_f32_e32 v57, v57
	v_exp_f32_e32 v58, v58
	v_exp_f32_e32 v59, v59
	v_exp_f32_e32 v60, v60
	v_exp_f32_e32 v61, v61
	v_exp_f32_e32 v62, v62
	v_exp_f32_e32 v63, v63
	v_exp_f32_e32 v64, v64
	v_exp_f32_e32 v65, v65
	s_nop 0
	v_add_f32_e32 v237, v2, v3
	v_add_f32_e32 v237, v237, v4
	v_add_f32_e32 v237, v237, v5
	v_add_f32_e32 v237, v237, v6
	v_add_f32_e32 v237, v237, v7
	v_add_f32_e32 v237, v237, v8
	v_add_f32_e32 v237, v237, v9
	v_add_f32_e32 v237, v237, v10
	v_add_f32_e32 v237, v237, v11
	v_add_f32_e32 v237, v237, v12
	v_add_f32_e32 v237, v237, v13
	v_add_f32_e32 v237, v237, v14
	v_add_f32_e32 v237, v237, v15
	v_add_f32_e32 v237, v237, v16
	v_add_f32_e32 v237, v237, v17
	v_add_f32_e32 v237, v237, v18
	v_add_f32_e32 v237, v237, v19
	v_add_f32_e32 v237, v237, v20
	v_add_f32_e32 v237, v237, v21
	v_add_f32_e32 v237, v237, v22
	v_add_f32_e32 v237, v237, v23
	v_add_f32_e32 v237, v237, v24
	v_add_f32_e32 v237, v237, v25
	v_add_f32_e32 v237, v237, v26
	v_add_f32_e32 v237, v237, v27
	v_add_f32_e32 v237, v237, v28
	v_add_f32_e32 v237, v237, v29
	v_add_f32_e32 v237, v237, v30
	v_add_f32_e32 v237, v237, v31
	v_add_f32_e32 v237, v237, v32
	v_add_f32_e32 v237, v237, v33
	v_add_f32_e32 v237, v237, v34
	v_add_f32_e32 v237, v237, v35
	v_add_f32_e32 v237, v237, v36
	v_add_f32_e32 v237, v237, v37
	v_add_f32_e32 v237, v237, v38
	v_add_f32_e32 v237, v237, v39
	v_add_f32_e32 v237, v237, v40
	v_add_f32_e32 v237, v237, v41
	v_add_f32_e32 v237, v237, v42
	v_add_f32_e32 v237, v237, v43
	v_add_f32_e32 v237, v237, v44
	v_add_f32_e32 v237, v237, v45
	v_add_f32_e32 v237, v237, v46
	v_add_f32_e32 v237, v237, v47
	v_add_f32_e32 v237, v237, v48
	v_add_f32_e32 v237, v237, v49
	v_add_f32_e32 v237, v237, v50
	v_add_f32_e32 v237, v237, v51
	v_add_f32_e32 v237, v237, v52
	v_add_f32_e32 v237, v237, v53
	v_add_f32_e32 v237, v237, v54
	v_add_f32_e32 v237, v237, v55
	v_add_f32_e32 v237, v237, v56
	v_add_f32_e32 v237, v237, v57
	v_add_f32_e32 v237, v237, v58
	v_add_f32_e32 v237, v237, v59
	v_add_f32_e32 v237, v237, v60
	v_add_f32_e32 v237, v237, v61
	v_add_f32_e32 v237, v237, v62
	v_add_f32_e32 v237, v237, v63
	v_add_f32_e32 v237, v237, v64
	v_add_f32_e32 v237, v237, v65
	ds_bpermute_b32 v248, v234, v237
	s_waitcnt lgkmcnt(0)
	v_add_f32_e32 v237, v237, v248
	ds_bpermute_b32 v248, v235, v237
	s_waitcnt lgkmcnt(0)
	v_add_f32_e32 v237, v237, v248
	v_rcp_f32_e32 v0, v237
	v_cvt_pk_bf16_f32 v162, v2, v3
	v_cvt_pk_bf16_f32 v163, v4, v5
	v_cvt_pk_bf16_f32 v164, v6, v7
	v_cvt_pk_bf16_f32 v165, v8, v9
	v_cvt_pk_bf16_f32 v166, v10, v11
	v_cvt_pk_bf16_f32 v167, v12, v13
	v_cvt_pk_bf16_f32 v168, v14, v15
	v_cvt_pk_bf16_f32 v169, v16, v17
	v_cvt_pk_bf16_f32 v170, v18, v19
	v_cvt_pk_bf16_f32 v171, v20, v21
	v_cvt_pk_bf16_f32 v172, v22, v23
	v_cvt_pk_bf16_f32 v173, v24, v25
	v_cvt_pk_bf16_f32 v174, v26, v27
	v_cvt_pk_bf16_f32 v175, v28, v29
	v_cvt_pk_bf16_f32 v176, v30, v31
	v_cvt_pk_bf16_f32 v177, v32, v33
	v_cvt_pk_bf16_f32 v178, v34, v35
	v_cvt_pk_bf16_f32 v179, v36, v37
	v_cvt_pk_bf16_f32 v180, v38, v39
	v_cvt_pk_bf16_f32 v181, v40, v41
	v_cvt_pk_bf16_f32 v182, v42, v43
	v_cvt_pk_bf16_f32 v183, v44, v45
	v_cvt_pk_bf16_f32 v184, v46, v47
	v_cvt_pk_bf16_f32 v185, v48, v49
	v_cvt_pk_bf16_f32 v186, v50, v51
	v_cvt_pk_bf16_f32 v187, v52, v53
	v_cvt_pk_bf16_f32 v188, v54, v55
	v_cvt_pk_bf16_f32 v189, v56, v57
	v_cvt_pk_bf16_f32 v190, v58, v59
	v_cvt_pk_bf16_f32 v191, v60, v61
	v_cvt_pk_bf16_f32 v192, v62, v63
	v_cvt_pk_bf16_f32 v193, v64, v65
	s_waitcnt vmcnt(0)
	s_barrier
	s_add_u32 s44, s42, 262144
	s_addc_u32 s45, s43, 0
	v_lshrrev_b32_e32 v237, 5, v236
	v_add_u32_e32 v237, 0, v237
	v_and_b32_e32 v248, 31, v236
	v_xor_b32_e32 v248, v248, v237
	v_lshl_add_u32 v237, s16, 4, v237
	v_lshlrev_b32_e32 v237, 11, v237
	v_lshl_add_u32 v237, v248, 4, v237
	s_add_u32 m0, s49, 65536
	s_nop 0
	global_load_lds_dwordx4 v237, s[44:45]
	v_lshrrev_b32_e32 v237, 5, v236
	v_add_u32_e32 v237, 2, v237
	v_and_b32_e32 v248, 31, v236
	v_xor_b32_e32 v248, v248, v237
	v_lshl_add_u32 v237, s16, 4, v237
	v_lshlrev_b32_e32 v237, 11, v237
	v_lshl_add_u32 v237, v248, 4, v237
	s_add_u32 m0, s49, 66560
	s_nop 0
	global_load_lds_dwordx4 v237, s[44:45]
	v_lshrrev_b32_e32 v237, 5, v236
	v_add_u32_e32 v237, 4, v237
	v_and_b32_e32 v248, 31, v236
	v_xor_b32_e32 v248, v248, v237
	v_lshl_add_u32 v237, s16, 4, v237
	v_lshlrev_b32_e32 v237, 11, v237
	v_lshl_add_u32 v237, v248, 4, v237
	s_add_u32 m0, s49, 67584
	s_nop 0
	global_load_lds_dwordx4 v237, s[44:45]
	v_lshrrev_b32_e32 v237, 5, v236
	v_add_u32_e32 v237, 6, v237
	v_and_b32_e32 v248, 31, v236
	v_xor_b32_e32 v248, v248, v237
	v_lshl_add_u32 v237, s16, 4, v237
	v_lshlrev_b32_e32 v237, 11, v237
	v_lshl_add_u32 v237, v248, 4, v237
	s_add_u32 m0, s49, 68608
	s_nop 0
	global_load_lds_dwordx4 v237, s[44:45]
	v_lshrrev_b32_e32 v237, 5, v236
	v_add_u32_e32 v237, 8, v237
	v_and_b32_e32 v248, 31, v236
	v_xor_b32_e32 v248, v248, v237
	v_lshl_add_u32 v237, s16, 4, v237
	v_lshlrev_b32_e32 v237, 11, v237
	v_lshl_add_u32 v237, v248, 4, v237
	s_add_u32 m0, s49, 69632
	s_nop 0
	global_load_lds_dwordx4 v237, s[44:45]
	v_lshrrev_b32_e32 v237, 5, v236
	v_add_u32_e32 v237, 10, v237
	v_and_b32_e32 v248, 31, v236
	v_xor_b32_e32 v248, v248, v237
	v_lshl_add_u32 v237, s16, 4, v237
	v_lshlrev_b32_e32 v237, 11, v237
	v_lshl_add_u32 v237, v248, 4, v237
	s_add_u32 m0, s49, 70656
	s_nop 0
	global_load_lds_dwordx4 v237, s[44:45]
	v_lshrrev_b32_e32 v237, 5, v236
	v_add_u32_e32 v237, 12, v237
	v_and_b32_e32 v248, 31, v236
	v_xor_b32_e32 v248, v248, v237
	v_lshl_add_u32 v237, s16, 4, v237
	v_lshlrev_b32_e32 v237, 11, v237
	v_lshl_add_u32 v237, v248, 4, v237
; #define LAS __attribute__((address_space(3)))
; #define MFMA16(a, b, c) __builtin_amdgcn_mfma_f32_16x16x32_bf16((a), (b), (c), 0, 0, 0)
; #define DSEC(k) do { if (PROBE_DSEC) { const unsigned long long tn_ = __builtin_amdgcn_s_memrealtime(); if (PROBE_DSEC == (k)) tsec += tn_ - tl_; tl_ = tn_; } } while (0)
; #define XV_LOAD(R, b_, h_, hh_) do { _Pragma("unroll") for (int i = 0; i < 8; ++i) { const int p = tid + 512 * i, dhr = p >> 5, c = p & 31; R[i] = *(const u32x4*)(memVT + (size_t)((h_) * 256 + 128 * (hh_) + dhr) * MROWS + (b_) * NMEM + 8 * c); } } while (0)
; #define XV_WRITE(R) do { _Pragma("unroll") for (int i = 0; i < 8; ++i) { const int p = tid + 512 * i, dhr = p >> 5, c = p & 31; u32x2 lo, hi; lo.x = R[i].x; lo.y = R[i].y; hi.x = R[i].z; hi.y = R[i].w; \
;         *(LAS u32x2*)(VL + vt_off(dhr, 2 * c)) = lo; *(LAS u32x2*)(VL + vt_off(dhr, 2 * c + 1)) = hi; } } while (0)
; DI void xattn_phase(LAS unsigned char* L, const bf16* Qx, const bf16* memK, const bf16* memVT, bf16* Ox, int G, int bid, int tid, unsigned long long& tsec) {
;     ...
;         for (int hh = 0; hh < 2; ++hh) {
;             if (hh == 1) { DSEC(14); __syncthreads(); XV_WRITE(rb); XV_LOAD(rb, bn, hn, 0); __syncthreads(); DSEC(15); }
;             f32x4 o[8];
; #pragma unroll
;             for (int dt = 0; dt < 8; ++dt) o[dt] = (f32x4){0.f, 0.f, 0.f, 0.f};
;             const unsigned x0 = (unsigned)(fq ^ (fr >> 3));
;             const LAS unsigned char* vev = L + KL_BYTES + fr * VSTR + (x0 << 3); const LAS unsigned char* vod = L + KL_BYTES + fr * VSTR + ((x0 ^ 2u) << 3);
; #pragma unroll
;             for (int pp = 0; pp < 8; ++pp)
; #pragma unroll
;                 for (int d4 = 0; d4 < 2; ++d4) { bf16x8 vf[4];
; #pragma unroll
;                     for (int dq = 0; dq < 4; ++dq) { const int dt = 4 * d4 + dq; const LAS unsigned char* vb_ = ((dt & 1) ? vod : vev) + 16 * dt * VSTR + 64 * pp;
;                         const s16x4 lo = *(const LAS s16x4*)(vb_ + (((2 * dt) & 4) << 3)), hi = *(const LAS s16x4*)(vb_ + ((((2 * dt) & 4) ^ 4) << 3)); vf[dq] = __builtin_shufflevector(lo, hi, 0, 1, 2, 3, 4, 5, 6, 7); }
; #pragma unroll
;                     for (int dq = 0; dq < 4; ++dq) o[4 * d4 + dq] = MFMA16(vf[dq], pf[pp], o[4 * d4 + dq]);
;                 }
	s_add_u32 m0, s49, 71680
	s_nop 0
	global_load_lds_dwordx4 v237, s[44:45]
	v_lshrrev_b32_e32 v237, 5, v236
	v_add_u32_e32 v237, 14, v237
	v_and_b32_e32 v248, 31, v236
	v_xor_b32_e32 v248, v248, v237
	v_lshl_add_u32 v237, s16, 4, v237
	v_lshlrev_b32_e32 v237, 11, v237
	v_lshl_add_u32 v237, v248, 4, v237
	s_add_u32 m0, s49, 72704
	s_nop 0
	global_load_lds_dwordx4 v237, s[44:45]
	ds_read_b64 v[98:99], v216 offset:0
	ds_read_b64 v[100:101], v217 offset:0
	ds_read_b64 v[102:103], v216 offset:8192
	ds_read_b64 v[104:105], v217 offset:8192
	ds_read_b64 v[106:107], v216 offset:16384
	ds_read_b64 v[108:109], v217 offset:16384
	ds_read_b64 v[110:111], v216 offset:24576
	ds_read_b64 v[112:113], v217 offset:24576
	ds_read_b64 v[114:115], v216 offset:32768
	ds_read_b64 v[116:117], v217 offset:32768
	ds_read_b64 v[118:119], v216 offset:40960
	ds_read_b64 v[120:121], v217 offset:40960
	ds_read_b64 v[122:123], v216 offset:49152
	ds_read_b64 v[124:125], v217 offset:49152
	ds_read_b64 v[126:127], v216 offset:57344
	ds_read_b64 v[128:129], v217 offset:57344
	ds_read_b64 v[130:131], v218 offset:0
	ds_read_b64 v[132:133], v219 offset:0
	ds_read_b64 v[134:135], v218 offset:8192
	ds_read_b64 v[136:137], v219 offset:8192
	ds_read_b64 v[138:139], v218 offset:16384
	ds_read_b64 v[140:141], v219 offset:16384
	ds_read_b64 v[142:143], v218 offset:24576
	ds_read_b64 v[144:145], v219 offset:24576
	ds_read_b64 v[146:147], v218 offset:32768
	ds_read_b64 v[148:149], v219 offset:32768
	ds_read_b64 v[150:151], v218 offset:40960
	ds_read_b64 v[152:153], v219 offset:40960
	ds_read_b64 v[154:155], v218 offset:49152
	ds_read_b64 v[156:157], v219 offset:49152
	ds_read_b64 v[158:159], v218 offset:57344
	ds_read_b64 v[160:161], v219 offset:57344
	s_waitcnt lgkmcnt(15)
	v_mfma_f32_16x16x32_bf16 v[2:5], v[98:101], v[162:165], 0
	ds_read_b64 v[98:99], v220 offset:0
	ds_read_b64 v[100:101], v221 offset:0
	v_mfma_f32_16x16x32_bf16 v[6:9], v[102:105], v[162:165], 0
	ds_read_b64 v[102:103], v220 offset:8192
	ds_read_b64 v[104:105], v221 offset:8192
	v_mfma_f32_16x16x32_bf16 v[10:13], v[106:109], v[162:165], 0
	ds_read_b64 v[106:107], v220 offset:16384
	ds_read_b64 v[108:109], v221 offset:16384
	v_mfma_f32_16x16x32_bf16 v[14:17], v[110:113], v[162:165], 0
	ds_read_b64 v[110:111], v220 offset:24576
	ds_read_b64 v[112:113], v221 offset:24576
	v_mfma_f32_16x16x32_bf16 v[18:21], v[114:117], v[162:165], 0
	ds_read_b64 v[114:115], v220 offset:32768
	ds_read_b64 v[116:117], v221 offset:32768
	v_mfma_f32_16x16x32_bf16 v[22:25], v[118:121], v[162:165], 0
	ds_read_b64 v[118:119], v220 offset:40960
	ds_read_b64 v[120:121], v221 offset:40960
	v_mfma_f32_16x16x32_bf16 v[26:29], v[122:125], v[162:165], 0
	ds_read_b64 v[122:123], v220 offset:49152
	ds_read_b64 v[124:125], v221 offset:49152
	v_mfma_f32_16x16x32_bf16 v[30:33], v[126:129], v[162:165], 0
	ds_read_b64 v[126:127], v220 offset:57344
	ds_read_b64 v[128:129], v221 offset:57344
	s_waitcnt lgkmcnt(15)
	v_mfma_f32_16x16x32_bf16 v[2:5], v[130:133], v[166:169], v[2:5]
	ds_read_b64 v[130:131], v222 offset:0
	ds_read_b64 v[132:133], v223 offset:0
	v_mfma_f32_16x16x32_bf16 v[6:9], v[134:137], v[166:169], v[6:9]
	ds_read_b64 v[134:135], v222 offset:8192
	ds_read_b64 v[136:137], v223 offset:8192
	v_mfma_f32_16x16x32_bf16 v[10:13], v[138:141], v[166:169], v[10:13]
	ds_read_b64 v[138:139], v222 offset:16384
	ds_read_b64 v[140:141], v223 offset:16384
	v_mfma_f32_16x16x32_bf16 v[14:17], v[142:145], v[166:169], v[14:17]
	ds_read_b64 v[142:143], v222 offset:24576
	ds_read_b64 v[144:145], v223 offset:24576
	v_mfma_f32_16x16x32_bf16 v[18:21], v[146:149], v[166:169], v[18:21]
	ds_read_b64 v[146:147], v222 offset:32768
	ds_read_b64 v[148:149], v223 offset:32768
	v_mfma_f32_16x16x32_bf16 v[22:25], v[150:153], v[166:169], v[22:25]
	ds_read_b64 v[150:151], v222 offset:40960
	ds_read_b64 v[152:153], v223 offset:40960
	v_mfma_f32_16x16x32_bf16 v[26:29], v[154:157], v[166:169], v[26:29]
	ds_read_b64 v[154:155], v222 offset:49152
	ds_read_b64 v[156:157], v223 offset:49152
	v_mfma_f32_16x16x32_bf16 v[30:33], v[158:161], v[166:169], v[30:33]
	ds_read_b64 v[158:159], v222 offset:57344
	ds_read_b64 v[160:161], v223 offset:57344
	s_waitcnt lgkmcnt(15)
	v_mfma_f32_16x16x32_bf16 v[2:5], v[98:101], v[170:173], v[2:5]
	ds_read_b64 v[98:99], v216 offset:256
	ds_read_b64 v[100:101], v217 offset:256
	v_mfma_f32_16x16x32_bf16 v[6:9], v[102:105], v[170:173], v[6:9]
	ds_read_b64 v[102:103], v216 offset:8448
	ds_read_b64 v[104:105], v217 offset:8448
	v_mfma_f32_16x16x32_bf16 v[10:13], v[106:109], v[170:173], v[10:13]
	ds_read_b64 v[106:107], v216 offset:16640
	ds_read_b64 v[108:109], v217 offset:16640
	v_mfma_f32_16x16x32_bf16 v[14:17], v[110:113], v[170:173], v[14:17]
	ds_read_b64 v[110:111], v216 offset:24832
	ds_read_b64 v[112:113], v217 offset:24832
	v_mfma_f32_16x16x32_bf16 v[18:21], v[114:117], v[170:173], v[18:21]
	ds_read_b64 v[114:115], v216 offset:33024
	ds_read_b64 v[116:117], v217 offset:33024
	v_mfma_f32_16x16x32_bf16 v[22:25], v[118:121], v[170:173], v[22:25]
	ds_read_b64 v[118:119], v216 offset:41216
	ds_read_b64 v[120:121], v217 offset:41216
	v_mfma_f32_16x16x32_bf16 v[26:29], v[122:125], v[170:173], v[26:29]
	ds_read_b64 v[122:123], v216 offset:49408
	ds_read_b64 v[124:125], v217 offset:49408
	v_mfma_f32_16x16x32_bf16 v[30:33], v[126:129], v[170:173], v[30:33]
	ds_read_b64 v[126:127], v216 offset:57600
	ds_read_b64 v[128:129], v217 offset:57600
	s_waitcnt lgkmcnt(15)
; #define LAS __attribute__((address_space(3)))
; #define MFMA16(a, b, c) __builtin_amdgcn_mfma_f32_16x16x32_bf16((a), (b), (c), 0, 0, 0)
; DI void xattn_phase(LAS unsigned char* L, const bf16* Qx, const bf16* memK, const bf16* memVT, bf16* Ox, int G, int bid, int tid, unsigned long long& tsec) {
;     ...
;     for (int unit = bid; unit < 512; unit += G) {
;         const int j = unit & 31, h = (unit >> 5) & 3, b = unit >> 7;
;         const int nun = unit + G < 512 ? unit + G : unit, hn = (nun >> 5) & 3, bn = nun >> 7;
;     ...
;             for (int pp = 0; pp < 8; ++pp)
; #pragma unroll
;                 for (int d4 = 0; d4 < 2; ++d4) { bf16x8 vf[4];
; #pragma unroll
;                     for (int dq = 0; dq < 4; ++dq) { const int dt = 4 * d4 + dq; const LAS unsigned char* vb_ = ((dt & 1) ? vod : vev) + 16 * dt * VSTR + 64 * pp;
;                         const s16x4 lo = *(const LAS s16x4*)(vb_ + (((2 * dt) & 4) << 3)), hi = *(const LAS s16x4*)(vb_ + ((((2 * dt) & 4) ^ 4) << 3)); vf[dq] = __builtin_shufflevector(lo, hi, 0, 1, 2, 3, 4, 5, 6, 7); }
; #pragma unroll
;                     for (int dq = 0; dq < 4; ++dq) o[4 * d4 + dq] = MFMA16(vf[dq], pf[pp], o[4 * d4 + dq]);
;                 }
	v_mfma_f32_16x16x32_bf16 v[2:5], v[130:133], v[174:177], v[2:5]
	ds_read_b64 v[130:131], v218 offset:256
	ds_read_b64 v[132:133], v219 offset:256
	v_mfma_f32_16x16x32_bf16 v[6:9], v[134:137], v[174:177], v[6:9]
	ds_read_b64 v[134:135], v218 offset:8448
	ds_read_b64 v[136:137], v219 offset:8448
	v_mfma_f32_16x16x32_bf16 v[10:13], v[138:141], v[174:177], v[10:13]
	ds_read_b64 v[138:139], v218 offset:16640
	ds_read_b64 v[140:141], v219 offset:16640
	v_mfma_f32_16x16x32_bf16 v[14:17], v[142:145], v[174:177], v[14:17]
	ds_read_b64 v[142:143], v218 offset:24832
	ds_read_b64 v[144:145], v219 offset:24832
	v_mfma_f32_16x16x32_bf16 v[18:21], v[146:149], v[174:177], v[18:21]
	ds_read_b64 v[146:147], v218 offset:33024
	ds_read_b64 v[148:149], v219 offset:33024
	v_mfma_f32_16x16x32_bf16 v[22:25], v[150:153], v[174:177], v[22:25]
	ds_read_b64 v[150:151], v218 offset:41216
	ds_read_b64 v[152:153], v219 offset:41216
	v_mfma_f32_16x16x32_bf16 v[26:29], v[154:157], v[174:177], v[26:29]
	ds_read_b64 v[154:155], v218 offset:49408
	ds_read_b64 v[156:157], v219 offset:49408
	v_mfma_f32_16x16x32_bf16 v[30:33], v[158:161], v[174:177], v[30:33]
	ds_read_b64 v[158:159], v218 offset:57600
	ds_read_b64 v[160:161], v219 offset:57600
	s_waitcnt lgkmcnt(15)
	v_mfma_f32_16x16x32_bf16 v[2:5], v[98:101], v[178:181], v[2:5]
	ds_read_b64 v[98:99], v220 offset:256
	ds_read_b64 v[100:101], v221 offset:256
	v_mfma_f32_16x16x32_bf16 v[6:9], v[102:105], v[178:181], v[6:9]
	ds_read_b64 v[102:103], v220 offset:8448
	ds_read_b64 v[104:105], v221 offset:8448
	v_mfma_f32_16x16x32_bf16 v[10:13], v[106:109], v[178:181], v[10:13]
	ds_read_b64 v[106:107], v220 offset:16640
	ds_read_b64 v[108:109], v221 offset:16640
	v_mfma_f32_16x16x32_bf16 v[14:17], v[110:113], v[178:181], v[14:17]
	ds_read_b64 v[110:111], v220 offset:24832
	ds_read_b64 v[112:113], v221 offset:24832
	v_mfma_f32_16x16x32_bf16 v[18:21], v[114:117], v[178:181], v[18:21]
	ds_read_b64 v[114:115], v220 offset:33024
	ds_read_b64 v[116:117], v221 offset:33024
	v_mfma_f32_16x16x32_bf16 v[22:25], v[118:121], v[178:181], v[22:25]
	ds_read_b64 v[118:119], v220 offset:41216
	ds_read_b64 v[120:121], v221 offset:41216
	v_mfma_f32_16x16x32_bf16 v[26:29], v[122:125], v[178:181], v[26:29]
	ds_read_b64 v[122:123], v220 offset:49408
	ds_read_b64 v[124:125], v221 offset:49408
	v_mfma_f32_16x16x32_bf16 v[30:33], v[126:129], v[178:181], v[30:33]
	ds_read_b64 v[126:127], v220 offset:57600
	ds_read_b64 v[128:129], v221 offset:57600
	s_waitcnt lgkmcnt(15)
	v_mfma_f32_16x16x32_bf16 v[2:5], v[130:133], v[182:185], v[2:5]
	ds_read_b64 v[130:131], v222 offset:256
	ds_read_b64 v[132:133], v223 offset:256
	v_mfma_f32_16x16x32_bf16 v[6:9], v[134:137], v[182:185], v[6:9]
	ds_read_b64 v[134:135], v222 offset:8448
	ds_read_b64 v[136:137], v223 offset:8448
	v_mfma_f32_16x16x32_bf16 v[10:13], v[138:141], v[182:185], v[10:13]
	ds_read_b64 v[138:139], v222 offset:16640
	ds_read_b64 v[140:141], v223 offset:16640
	v_mfma_f32_16x16x32_bf16 v[14:17], v[142:145], v[182:185], v[14:17]
	ds_read_b64 v[142:143], v222 offset:24832
	ds_read_b64 v[144:145], v223 offset:24832
	v_mfma_f32_16x16x32_bf16 v[18:21], v[146:149], v[182:185], v[18:21]
	ds_read_b64 v[146:147], v222 offset:33024
	ds_read_b64 v[148:149], v223 offset:33024
	v_mfma_f32_16x16x32_bf16 v[22:25], v[150:153], v[182:185], v[22:25]
	ds_read_b64 v[150:151], v222 offset:41216
	ds_read_b64 v[152:153], v223 offset:41216
	v_mfma_f32_16x16x32_bf16 v[26:29], v[154:157], v[182:185], v[26:29]
	ds_read_b64 v[154:155], v222 offset:49408
	ds_read_b64 v[156:157], v223 offset:49408
	v_mfma_f32_16x16x32_bf16 v[30:33], v[158:161], v[182:185], v[30:33]
	ds_read_b64 v[158:159], v222 offset:57600
	ds_read_b64 v[160:161], v223 offset:57600
	s_waitcnt lgkmcnt(15)
	v_mfma_f32_16x16x32_bf16 v[2:5], v[98:101], v[186:189], v[2:5]
	v_mfma_f32_16x16x32_bf16 v[6:9], v[102:105], v[186:189], v[6:9]
	v_mfma_f32_16x16x32_bf16 v[10:13], v[106:109], v[186:189], v[10:13]
	v_mfma_f32_16x16x32_bf16 v[14:17], v[110:113], v[186:189], v[14:17]
	v_mfma_f32_16x16x32_bf16 v[18:21], v[114:117], v[186:189], v[18:21]
	v_mfma_f32_16x16x32_bf16 v[22:25], v[118:121], v[186:189], v[22:25]
	v_mfma_f32_16x16x32_bf16 v[26:29], v[122:125], v[186:189], v[26:29]
	v_mfma_f32_16x16x32_bf16 v[30:33], v[126:129], v[186:189], v[30:33]
	s_waitcnt lgkmcnt(0)
	v_mfma_f32_16x16x32_bf16 v[2:5], v[130:133], v[190:193], v[2:5]
	v_mfma_f32_16x16x32_bf16 v[6:9], v[134:137], v[190:193], v[6:9]
	v_mfma_f32_16x16x32_bf16 v[10:13], v[138:141], v[190:193], v[10:13]
	v_mfma_f32_16x16x32_bf16 v[14:17], v[142:145], v[190:193], v[14:17]
	v_mfma_f32_16x16x32_bf16 v[18:21], v[146:149], v[190:193], v[18:21]
	v_mfma_f32_16x16x32_bf16 v[22:25], v[150:153], v[190:193], v[22:25]
	v_mfma_f32_16x16x32_bf16 v[26:29], v[154:157], v[190:193], v[26:29]
	v_mfma_f32_16x16x32_bf16 v[30:33], v[158:161], v[190:193], v[30:33]
	s_waitcnt vmcnt(0)
	s_barrier
	s_add_u32 s18, s17, 32
	s_bitcmp1_b32 s18, 5
	s_cbranch_scc0 .Lxa_last
; #define LAS __attribute__((address_space(3)))
; #define MFMA16(a, b, c) __builtin_amdgcn_mfma_f32_16x16x32_bf16((a), (b), (c), 0, 0, 0)
; #define XK_LOAD(R, b_, h_, hh_) do { _Pragma("unroll") for (int i = 0; i < 8; ++i) { const int p = tid + 512 * i, m = p >> 4, cb = p & 15; R[i] = *(const u32x4*)(memK + (size_t)((b_) * NMEM + m) * D + (h_) * 256 + 128 * (hh_) + 8 * cb); } } while (0)
; #define XV_LOAD(R, b_, h_, hh_) do { _Pragma("unroll") for (int i = 0; i < 8; ++i) { const int p = tid + 512 * i, dhr = p >> 5, c = p & 31; R[i] = *(const u32x4*)(memVT + (size_t)((h_) * 256 + 128 * (hh_) + dhr) * MROWS + (b_) * NMEM + 8 * c); } } while (0)
; DI void xattn_phase(LAS unsigned char* L, const bf16* Qx, const bf16* memK, const bf16* memVT, bf16* Ox, int G, int bid, int tid, unsigned long long& tsec) {
;     ...
;     if (bid < 512) { const int h0 = (bid >> 5) & 3, b0 = bid >> 7; XK_LOAD(ra, b0, h0, 0); XV_LOAD(rb, b0, h0, 0); }
;     for (int unit = bid; unit < 512; unit += G) {
;         const int j = unit & 31, h = (unit >> 5) & 3, b = unit >> 7;
;         const int nun = unit + G < 512 ? unit + G : unit, hn = (nun >> 5) & 3, bn = nun >> 7;
;         asm volatile("" : "+v"(ra[0]), "+v"(ra[1]), "+v"(ra[2]), "+v"(ra[3]), "+v"(ra[4]), "+v"(ra[5]), "+v"(ra[6]), "+v"(ra[7]));
;         asm volatile("" : "+v"(rb[0]), "+v"(rb[1]), "+v"(rb[2]), "+v"(rb[3]), "+v"(rb[4]), "+v"(rb[5]), "+v"(rb[6]), "+v"(rb[7]));
;         const int tok0 = b * T + 128 * j; const size_t tq = (size_t)(tok0 + 16 * wid + fr);
;     ...
;             for (int pp = 0; pp < 8; ++pp)
; #pragma unroll
;                 for (int d4 = 0; d4 < 2; ++d4) { bf16x8 vf[4];
; #pragma unroll
;                     for (int dq = 0; dq < 4; ++dq) { const int dt = 4 * d4 + dq; const LAS unsigned char* vb_ = ((dt & 1) ? vod : vev) + 16 * dt * VSTR + 64 * pp;
;                         const s16x4 lo = *(const LAS s16x4*)(vb_ + (((2 * dt) & 4) << 3)), hi = *(const LAS s16x4*)(vb_ + ((((2 * dt) & 4) ^ 4) << 3)); vf[dq] = __builtin_shufflevector(lo, hi, 0, 1, 2, 3, 4, 5, 6, 7); }
; #pragma unroll
;                     for (int dq = 0; dq < 4; ++dq) o[4 * d4 + dq] = MFMA16(vf[dq], pf[pp], o[4 * d4 + dq]);
;                 }
	s_and_b32 s44, s18, 31
	s_bfe_u32 s45, s18, 0x20005
	s_lshr_b32 s46, s18, 7
	s_lshl_b32 s47, s46, 12
	s_lshl_b32 s44, s44, 7
	s_add_u32 s47, s47, s44
	s_lshl_b32 s47, s47, 11
	s_lshl_b32 s44, s45, 9
	s_add_u32 s47, s47, s44
	s_add_u32 s20, s0, s47
	s_addc_u32 s21, s1, 0
	s_lshl_b32 s47, s46, 19
	s_add_u32 s47, s47, s44
	s_add_u32 s24, s36, s47
	s_addc_u32 s25, s37, 0
	s_lshl_b32 s47, s45, 19
	s_lshl_b32 s44, s46, 9
	s_add_u32 s47, s47, s44
	s_add_u32 s42, s2, s47
	s_addc_u32 s43, s3, 0
	s_add_u32 s44, s24, 0
	s_addc_u32 s45, s25, 0
	s_add_u32 s46, s44, 0x8000
	s_addc_u32 s47, s45, 0
	s_add_u32 m0, s49, 0
	s_nop 0
	global_load_lds_dwordx4 v198, s[44:45]
	s_add_u32 m0, s49, 1024
	s_nop 0
	global_load_lds_dwordx4 v199, s[44:45]
	s_add_u32 m0, s49, 2048
	s_nop 0
	global_load_lds_dwordx4 v200, s[44:45]
	s_add_u32 m0, s49, 3072
	s_nop 0
	global_load_lds_dwordx4 v201, s[44:45]
	s_add_u32 m0, s49, 4096
	s_nop 0
	global_load_lds_dwordx4 v198, s[46:47]
	s_add_u32 m0, s49, 5120
	s_nop 0
	global_load_lds_dwordx4 v199, s[46:47]
	s_add_u32 m0, s49, 6144
	s_nop 0
	global_load_lds_dwordx4 v200, s[46:47]
	s_add_u32 m0, s49, 7168
	s_nop 0
	global_load_lds_dwordx4 v201, s[46:47]
	global_load_dwordx4 v[66:69], v232, s[20:21]
	global_load_dwordx4 v[70:73], v232, s[20:21] offset:64
	global_load_dwordx4 v[74:77], v232, s[20:21] offset:128
	global_load_dwordx4 v[78:81], v232, s[20:21] offset:192
	global_load_dwordx4 v[82:85], v232, s[20:21] offset:256
	global_load_dwordx4 v[86:89], v232, s[20:21] offset:320
	global_load_dwordx4 v[90:93], v232, s[20:21] offset:384
	global_load_dwordx4 v[94:97], v232, s[20:21] offset:448
	ds_read_b64 v[98:99], v224 offset:0
	ds_read_b64 v[100:101], v225 offset:0
	ds_read_b64 v[102:103], v224 offset:8192
	ds_read_b64 v[104:105], v225 offset:8192
	ds_read_b64 v[106:107], v224 offset:16384
	ds_read_b64 v[108:109], v225 offset:16384
	ds_read_b64 v[110:111], v224 offset:24576
	ds_read_b64 v[112:113], v225 offset:24576
	ds_read_b64 v[114:115], v224 offset:32768
	ds_read_b64 v[116:117], v225 offset:32768
	ds_read_b64 v[118:119], v224 offset:40960
	ds_read_b64 v[120:121], v225 offset:40960
	ds_read_b64 v[122:123], v224 offset:49152
	ds_read_b64 v[124:125], v225 offset:49152
	ds_read_b64 v[126:127], v224 offset:57344
	ds_read_b64 v[128:129], v225 offset:57344
	ds_read_b64 v[130:131], v226 offset:0
	ds_read_b64 v[132:133], v227 offset:0
	ds_read_b64 v[134:135], v226 offset:8192
	ds_read_b64 v[136:137], v227 offset:8192
	ds_read_b64 v[138:139], v226 offset:16384
	ds_read_b64 v[140:141], v227 offset:16384
	ds_read_b64 v[142:143], v226 offset:24576
	ds_read_b64 v[144:145], v227 offset:24576
	ds_read_b64 v[146:147], v226 offset:32768
	ds_read_b64 v[148:149], v227 offset:32768
	ds_read_b64 v[150:151], v226 offset:40960
	ds_read_b64 v[152:153], v227 offset:40960
	ds_read_b64 v[154:155], v226 offset:49152
	ds_read_b64 v[156:157], v227 offset:49152
	ds_read_b64 v[158:159], v226 offset:57344
	ds_read_b64 v[160:161], v227 offset:57344
	s_waitcnt lgkmcnt(15)
	v_mfma_f32_16x16x32_bf16 v[34:37], v[98:101], v[162:165], 0
	ds_read_b64 v[98:99], v228 offset:0
	ds_read_b64 v[100:101], v229 offset:0
	v_mfma_f32_16x16x32_bf16 v[38:41], v[102:105], v[162:165], 0
	ds_read_b64 v[102:103], v228 offset:8192
	ds_read_b64 v[104:105], v229 offset:8192
	v_mfma_f32_16x16x32_bf16 v[42:45], v[106:109], v[162:165], 0
	ds_read_b64 v[106:107], v228 offset:16384
	ds_read_b64 v[108:109], v229 offset:16384
	v_mfma_f32_16x16x32_bf16 v[46:49], v[110:113], v[162:165], 0
	ds_read_b64 v[110:111], v228 offset:24576
	ds_read_b64 v[112:113], v229 offset:24576
	v_mfma_f32_16x16x32_bf16 v[50:53], v[114:117], v[162:165], 0
	ds_read_b64 v[114:115], v228 offset:32768
	ds_read_b64 v[116:117], v229 offset:32768
	v_mfma_f32_16x16x32_bf16 v[54:57], v[118:121], v[162:165], 0
	ds_read_b64 v[118:119], v228 offset:40960
	ds_read_b64 v[120:121], v229 offset:40960
	v_mfma_f32_16x16x32_bf16 v[58:61], v[122:125], v[162:165], 0
	ds_read_b64 v[122:123], v228 offset:49152
	ds_read_b64 v[124:125], v229 offset:49152
	v_mfma_f32_16x16x32_bf16 v[62:65], v[126:129], v[162:165], 0
	ds_read_b64 v[126:127], v228 offset:57344
	ds_read_b64 v[128:129], v229 offset:57344
	s_waitcnt lgkmcnt(15)
	v_mfma_f32_16x16x32_bf16 v[34:37], v[130:133], v[166:169], v[34:37]
	ds_read_b64 v[130:131], v230 offset:0
	ds_read_b64 v[132:133], v231 offset:0
	v_mfma_f32_16x16x32_bf16 v[38:41], v[134:137], v[166:169], v[38:41]
	ds_read_b64 v[134:135], v230 offset:8192
	ds_read_b64 v[136:137], v231 offset:8192
	v_mfma_f32_16x16x32_bf16 v[42:45], v[138:141], v[166:169], v[42:45]
	ds_read_b64 v[138:139], v230 offset:16384
	ds_read_b64 v[140:141], v231 offset:16384
	v_mfma_f32_16x16x32_bf16 v[46:49], v[142:145], v[166:169], v[46:49]
	ds_read_b64 v[142:143], v230 offset:24576
	ds_read_b64 v[144:145], v231 offset:24576
	v_mfma_f32_16x16x32_bf16 v[50:53], v[146:149], v[166:169], v[50:53]
	ds_read_b64 v[146:147], v230 offset:32768
	ds_read_b64 v[148:149], v231 offset:32768
	v_mfma_f32_16x16x32_bf16 v[54:57], v[150:153], v[166:169], v[54:57]
	ds_read_b64 v[150:151], v230 offset:40960
	ds_read_b64 v[152:153], v231 offset:40960
	v_mfma_f32_16x16x32_bf16 v[58:61], v[154:157], v[166:169], v[58:61]
	ds_read_b64 v[154:155], v230 offset:49152
	ds_read_b64 v[156:157], v231 offset:49152
	v_mfma_f32_16x16x32_bf16 v[62:65], v[158:161], v[166:169], v[62:65]
	ds_read_b64 v[158:159], v230 offset:57344
	ds_read_b64 v[160:161], v231 offset:57344
	s_waitcnt lgkmcnt(15)
; #define LAS __attribute__((address_space(3)))
; #define MFMA16(a, b, c) __builtin_amdgcn_mfma_f32_16x16x32_bf16((a), (b), (c), 0, 0, 0)
; DI void xattn_phase(LAS unsigned char* L, const bf16* Qx, const bf16* memK, const bf16* memVT, bf16* Ox, int G, int bid, int tid, unsigned long long& tsec) {
;     ...
;             for (int pp = 0; pp < 8; ++pp)
; #pragma unroll
;                 for (int d4 = 0; d4 < 2; ++d4) { bf16x8 vf[4];
; #pragma unroll
;                     for (int dq = 0; dq < 4; ++dq) { const int dt = 4 * d4 + dq; const LAS unsigned char* vb_ = ((dt & 1) ? vod : vev) + 16 * dt * VSTR + 64 * pp;
;                         const s16x4 lo = *(const LAS s16x4*)(vb_ + (((2 * dt) & 4) << 3)), hi = *(const LAS s16x4*)(vb_ + ((((2 * dt) & 4) ^ 4) << 3)); vf[dq] = __builtin_shufflevector(lo, hi, 0, 1, 2, 3, 4, 5, 6, 7); }
; #pragma unroll
;                     for (int dq = 0; dq < 4; ++dq) o[4 * d4 + dq] = MFMA16(vf[dq], pf[pp], o[4 * d4 + dq]);
;                 }
	v_mfma_f32_16x16x32_bf16 v[34:37], v[98:101], v[170:173], v[34:37]
	ds_read_b64 v[98:99], v224 offset:256
	ds_read_b64 v[100:101], v225 offset:256
	v_mfma_f32_16x16x32_bf16 v[38:41], v[102:105], v[170:173], v[38:41]
	ds_read_b64 v[102:103], v224 offset:8448
	ds_read_b64 v[104:105], v225 offset:8448
	v_mfma_f32_16x16x32_bf16 v[42:45], v[106:109], v[170:173], v[42:45]
	ds_read_b64 v[106:107], v224 offset:16640
	ds_read_b64 v[108:109], v225 offset:16640
	v_mfma_f32_16x16x32_bf16 v[46:49], v[110:113], v[170:173], v[46:49]
	ds_read_b64 v[110:111], v224 offset:24832
	ds_read_b64 v[112:113], v225 offset:24832
	v_mfma_f32_16x16x32_bf16 v[50:53], v[114:117], v[170:173], v[50:53]
	ds_read_b64 v[114:115], v224 offset:33024
	ds_read_b64 v[116:117], v225 offset:33024
	v_mfma_f32_16x16x32_bf16 v[54:57], v[118:121], v[170:173], v[54:57]
	ds_read_b64 v[118:119], v224 offset:41216
	ds_read_b64 v[120:121], v225 offset:41216
	v_mfma_f32_16x16x32_bf16 v[58:61], v[122:125], v[170:173], v[58:61]
	ds_read_b64 v[122:123], v224 offset:49408
	ds_read_b64 v[124:125], v225 offset:49408
	v_mfma_f32_16x16x32_bf16 v[62:65], v[126:129], v[170:173], v[62:65]
	ds_read_b64 v[126:127], v224 offset:57600
	ds_read_b64 v[128:129], v225 offset:57600
	s_waitcnt lgkmcnt(15)
	v_mfma_f32_16x16x32_bf16 v[34:37], v[130:133], v[174:177], v[34:37]
	ds_read_b64 v[130:131], v226 offset:256
	ds_read_b64 v[132:133], v227 offset:256
	v_mfma_f32_16x16x32_bf16 v[38:41], v[134:137], v[174:177], v[38:41]
	ds_read_b64 v[134:135], v226 offset:8448
	ds_read_b64 v[136:137], v227 offset:8448
	v_mfma_f32_16x16x32_bf16 v[42:45], v[138:141], v[174:177], v[42:45]
	ds_read_b64 v[138:139], v226 offset:16640
	ds_read_b64 v[140:141], v227 offset:16640
	v_mfma_f32_16x16x32_bf16 v[46:49], v[142:145], v[174:177], v[46:49]
	ds_read_b64 v[142:143], v226 offset:24832
	ds_read_b64 v[144:145], v227 offset:24832
	v_mfma_f32_16x16x32_bf16 v[50:53], v[146:149], v[174:177], v[50:53]
	ds_read_b64 v[146:147], v226 offset:33024
	ds_read_b64 v[148:149], v227 offset:33024
	v_mfma_f32_16x16x32_bf16 v[54:57], v[150:153], v[174:177], v[54:57]
	ds_read_b64 v[150:151], v226 offset:41216
	ds_read_b64 v[152:153], v227 offset:41216
	v_mfma_f32_16x16x32_bf16 v[58:61], v[154:157], v[174:177], v[58:61]
	ds_read_b64 v[154:155], v226 offset:49408
	ds_read_b64 v[156:157], v227 offset:49408
	v_mfma_f32_16x16x32_bf16 v[62:65], v[158:161], v[174:177], v[62:65]
	ds_read_b64 v[158:159], v226 offset:57600
	ds_read_b64 v[160:161], v227 offset:57600
	s_waitcnt lgkmcnt(15)
	v_mfma_f32_16x16x32_bf16 v[34:37], v[98:101], v[178:181], v[34:37]
	ds_read_b64 v[98:99], v228 offset:256
	ds_read_b64 v[100:101], v229 offset:256
	v_mfma_f32_16x16x32_bf16 v[38:41], v[102:105], v[178:181], v[38:41]
	ds_read_b64 v[102:103], v228 offset:8448
	ds_read_b64 v[104:105], v229 offset:8448
	v_mfma_f32_16x16x32_bf16 v[42:45], v[106:109], v[178:181], v[42:45]
	ds_read_b64 v[106:107], v228 offset:16640
	ds_read_b64 v[108:109], v229 offset:16640
	v_mfma_f32_16x16x32_bf16 v[46:49], v[110:113], v[178:181], v[46:49]
	ds_read_b64 v[110:111], v228 offset:24832
	ds_read_b64 v[112:113], v229 offset:24832
	v_mfma_f32_16x16x32_bf16 v[50:53], v[114:117], v[178:181], v[50:53]
	ds_read_b64 v[114:115], v228 offset:33024
	ds_read_b64 v[116:117], v229 offset:33024
	v_mfma_f32_16x16x32_bf16 v[54:57], v[118:121], v[178:181], v[54:57]
	ds_read_b64 v[118:119], v228 offset:41216
	ds_read_b64 v[120:121], v229 offset:41216
	v_mfma_f32_16x16x32_bf16 v[58:61], v[122:125], v[178:181], v[58:61]
	ds_read_b64 v[122:123], v228 offset:49408
	ds_read_b64 v[124:125], v229 offset:49408
	v_mfma_f32_16x16x32_bf16 v[62:65], v[126:129], v[178:181], v[62:65]
	ds_read_b64 v[126:127], v228 offset:57600
	ds_read_b64 v[128:129], v229 offset:57600
	s_waitcnt lgkmcnt(15)
	v_mfma_f32_16x16x32_bf16 v[34:37], v[130:133], v[182:185], v[34:37]
	ds_read_b64 v[130:131], v230 offset:256
	ds_read_b64 v[132:133], v231 offset:256
	v_mfma_f32_16x16x32_bf16 v[38:41], v[134:137], v[182:185], v[38:41]
	ds_read_b64 v[134:135], v230 offset:8448
	ds_read_b64 v[136:137], v231 offset:8448
	v_mfma_f32_16x16x32_bf16 v[42:45], v[138:141], v[182:185], v[42:45]
	ds_read_b64 v[138:139], v230 offset:16640
	ds_read_b64 v[140:141], v231 offset:16640
	v_mfma_f32_16x16x32_bf16 v[46:49], v[142:145], v[182:185], v[46:49]
	ds_read_b64 v[142:143], v230 offset:24832
	ds_read_b64 v[144:145], v231 offset:24832
	v_mfma_f32_16x16x32_bf16 v[50:53], v[146:149], v[182:185], v[50:53]
	ds_read_b64 v[146:147], v230 offset:33024
	ds_read_b64 v[148:149], v231 offset:33024
	v_mfma_f32_16x16x32_bf16 v[54:57], v[150:153], v[182:185], v[54:57]
	ds_read_b64 v[150:151], v230 offset:41216
	ds_read_b64 v[152:153], v231 offset:41216
	v_mfma_f32_16x16x32_bf16 v[58:61], v[154:157], v[182:185], v[58:61]
	ds_read_b64 v[154:155], v230 offset:49408
	ds_read_b64 v[156:157], v231 offset:49408
	v_mfma_f32_16x16x32_bf16 v[62:65], v[158:161], v[182:185], v[62:65]
	ds_read_b64 v[158:159], v230 offset:57600
	ds_read_b64 v[160:161], v231 offset:57600
	s_waitcnt lgkmcnt(15)
; DI unsigned pk2(float lo, float hi) { const bf2_t r = __builtin_convertvector((f32x2_t){lo, hi}, bf2_t); return __builtin_bit_cast(unsigned, r); }
; #define MFMA16(a, b, c) __builtin_amdgcn_mfma_f32_16x16x32_bf16((a), (b), (c), 0, 0, 0)
; #define DSEC(k) do { if (PROBE_DSEC) { const unsigned long long tn_ = __builtin_amdgcn_s_memrealtime(); if (PROBE_DSEC == (k)) tsec += tn_ - tl_; tl_ = tn_; } } while (0)
; DI void xattn_phase(LAS unsigned char* L, const bf16* Qx, const bf16* memK, const bf16* memVT, bf16* Ox, int G, int bid, int tid, unsigned long long& tsec) {
;     ...
;                     for (int dq = 0; dq < 4; ++dq) o[4 * d4 + dq] = MFMA16(vf[dq], pf[pp], o[4 * d4 + dq]);
;                 }
;             { bf16* op = Ox + tq * D + h * 256 + 128 * hh + 4 * fq;
; #pragma unroll
;               for (int dt = 0; dt < 8; ++dt) *(unsigned long long*)(op + 16 * dt) = (unsigned long long)pk2(o[dt][0] * inv, o[dt][1] * inv) | ((unsigned long long)pk2(o[dt][2] * inv, o[dt][3] * inv) << 32); }
;         }
;         DSEC(14);
	v_mfma_f32_16x16x32_bf16 v[34:37], v[98:101], v[186:189], v[34:37]
	v_mfma_f32_16x16x32_bf16 v[38:41], v[102:105], v[186:189], v[38:41]
	v_mfma_f32_16x16x32_bf16 v[42:45], v[106:109], v[186:189], v[42:45]
	v_mfma_f32_16x16x32_bf16 v[46:49], v[110:113], v[186:189], v[46:49]
	v_mfma_f32_16x16x32_bf16 v[50:53], v[114:117], v[186:189], v[50:53]
	v_mfma_f32_16x16x32_bf16 v[54:57], v[118:121], v[186:189], v[54:57]
	v_mfma_f32_16x16x32_bf16 v[58:61], v[122:125], v[186:189], v[58:61]
	v_mfma_f32_16x16x32_bf16 v[62:65], v[126:129], v[186:189], v[62:65]
	s_waitcnt lgkmcnt(0)
	v_mfma_f32_16x16x32_bf16 v[34:37], v[130:133], v[190:193], v[34:37]
	v_mfma_f32_16x16x32_bf16 v[38:41], v[134:137], v[190:193], v[38:41]
	v_mfma_f32_16x16x32_bf16 v[42:45], v[138:141], v[190:193], v[42:45]
	v_mfma_f32_16x16x32_bf16 v[46:49], v[142:145], v[190:193], v[46:49]
	v_mfma_f32_16x16x32_bf16 v[50:53], v[146:149], v[190:193], v[50:53]
	v_mfma_f32_16x16x32_bf16 v[54:57], v[150:153], v[190:193], v[54:57]
	v_mfma_f32_16x16x32_bf16 v[58:61], v[154:157], v[190:193], v[58:61]
	v_mfma_f32_16x16x32_bf16 v[62:65], v[158:161], v[190:193], v[62:65]
	v_mul_f32_e32 v2, v0, v2
	v_mul_f32_e32 v3, v0, v3
	v_mul_f32_e32 v4, v0, v4
	v_mul_f32_e32 v5, v0, v5
	v_cvt_pk_bf16_f32 v2, v2, v3
	v_cvt_pk_bf16_f32 v3, v4, v5
	global_store_dwordx2 v233, v[2:3], s[22:23]
	v_mul_f32_e32 v6, v0, v6
	v_mul_f32_e32 v7, v0, v7
	v_mul_f32_e32 v8, v0, v8
	v_mul_f32_e32 v9, v0, v9
	v_cvt_pk_bf16_f32 v6, v6, v7
	v_cvt_pk_bf16_f32 v7, v8, v9
	global_store_dwordx2 v233, v[6:7], s[22:23] offset:32
	v_mul_f32_e32 v10, v0, v10
	v_mul_f32_e32 v11, v0, v11
	v_mul_f32_e32 v12, v0, v12
	v_mul_f32_e32 v13, v0, v13
	v_cvt_pk_bf16_f32 v10, v10, v11
	v_cvt_pk_bf16_f32 v11, v12, v13
	global_store_dwordx2 v233, v[10:11], s[22:23] offset:64
	v_mul_f32_e32 v14, v0, v14
	v_mul_f32_e32 v15, v0, v15
	v_mul_f32_e32 v16, v0, v16
	v_mul_f32_e32 v17, v0, v17
	v_cvt_pk_bf16_f32 v14, v14, v15
	v_cvt_pk_bf16_f32 v15, v16, v17
	global_store_dwordx2 v233, v[14:15], s[22:23] offset:96
	v_mul_f32_e32 v18, v0, v18
	v_mul_f32_e32 v19, v0, v19
	v_mul_f32_e32 v20, v0, v20
	v_mul_f32_e32 v21, v0, v21
	v_cvt_pk_bf16_f32 v18, v18, v19
	v_cvt_pk_bf16_f32 v19, v20, v21
	global_store_dwordx2 v233, v[18:19], s[22:23] offset:128
	v_mul_f32_e32 v22, v0, v22
	v_mul_f32_e32 v23, v0, v23
	v_mul_f32_e32 v24, v0, v24
	v_mul_f32_e32 v25, v0, v25
	v_cvt_pk_bf16_f32 v22, v22, v23
	v_cvt_pk_bf16_f32 v23, v24, v25
	global_store_dwordx2 v233, v[22:23], s[22:23] offset:160
	v_mul_f32_e32 v26, v0, v26
	v_mul_f32_e32 v27, v0, v27
	v_mul_f32_e32 v28, v0, v28
	v_mul_f32_e32 v29, v0, v29
	v_cvt_pk_bf16_f32 v26, v26, v27
	v_cvt_pk_bf16_f32 v27, v28, v29
	global_store_dwordx2 v233, v[26:27], s[22:23] offset:192
	v_mul_f32_e32 v30, v0, v30
	v_mul_f32_e32 v31, v0, v31
	v_mul_f32_e32 v32, v0, v32
	v_mul_f32_e32 v33, v0, v33
	v_cvt_pk_bf16_f32 v30, v30, v31
	v_cvt_pk_bf16_f32 v31, v32, v33
	global_store_dwordx2 v233, v[30:31], s[22:23] offset:224
	v_mul_f32_e32 v34, v0, v34
	v_mul_f32_e32 v35, v0, v35
	v_mul_f32_e32 v36, v0, v36
	v_mul_f32_e32 v37, v0, v37
	v_cvt_pk_bf16_f32 v34, v34, v35
	v_cvt_pk_bf16_f32 v35, v36, v37
	global_store_dwordx2 v233, v[34:35], s[22:23] offset:256
	v_mul_f32_e32 v38, v0, v38
	v_mul_f32_e32 v39, v0, v39
	v_mul_f32_e32 v40, v0, v40
	v_mul_f32_e32 v41, v0, v41
	v_cvt_pk_bf16_f32 v38, v38, v39
	v_cvt_pk_bf16_f32 v39, v40, v41
	global_store_dwordx2 v233, v[38:39], s[22:23] offset:288
	v_mul_f32_e32 v42, v0, v42
	v_mul_f32_e32 v43, v0, v43
	v_mul_f32_e32 v44, v0, v44
	v_mul_f32_e32 v45, v0, v45
	v_cvt_pk_bf16_f32 v42, v42, v43
	v_cvt_pk_bf16_f32 v43, v44, v45
	global_store_dwordx2 v233, v[42:43], s[22:23] offset:320
	v_mul_f32_e32 v46, v0, v46
	v_mul_f32_e32 v47, v0, v47
	v_mul_f32_e32 v48, v0, v48
	v_mul_f32_e32 v49, v0, v49
	v_cvt_pk_bf16_f32 v46, v46, v47
	v_cvt_pk_bf16_f32 v47, v48, v49
	global_store_dwordx2 v233, v[46:47], s[22:23] offset:352
	v_mul_f32_e32 v50, v0, v50
	v_mul_f32_e32 v51, v0, v51
	v_mul_f32_e32 v52, v0, v52
	v_mul_f32_e32 v53, v0, v53
	v_cvt_pk_bf16_f32 v50, v50, v51
	v_cvt_pk_bf16_f32 v51, v52, v53
	global_store_dwordx2 v233, v[50:51], s[22:23] offset:384
	v_mul_f32_e32 v54, v0, v54
	v_mul_f32_e32 v55, v0, v55
	v_mul_f32_e32 v56, v0, v56
	v_mul_f32_e32 v57, v0, v57
	v_cvt_pk_bf16_f32 v54, v54, v55
	v_cvt_pk_bf16_f32 v55, v56, v57
	global_store_dwordx2 v233, v[54:55], s[22:23] offset:416
	v_mul_f32_e32 v58, v0, v58
	v_mul_f32_e32 v59, v0, v59
	v_mul_f32_e32 v60, v0, v60
	v_mul_f32_e32 v61, v0, v61
	v_cvt_pk_bf16_f32 v58, v58, v59
	v_cvt_pk_bf16_f32 v59, v60, v61
	global_store_dwordx2 v233, v[58:59], s[22:23] offset:448
	v_mul_f32_e32 v62, v0, v62
	v_mul_f32_e32 v63, v0, v63
	v_mul_f32_e32 v64, v0, v64
	v_mul_f32_e32 v65, v0, v65
	v_cvt_pk_bf16_f32 v62, v62, v63
	v_cvt_pk_bf16_f32 v63, v64, v65
	global_store_dwordx2 v233, v[62:63], s[22:23] offset:480
	s_mov_b32 s17, s18
	s_and_b32 s44, s17, 31
	s_bfe_u32 s45, s17, 0x20005
	s_lshr_b32 s46, s17, 7
	s_lshl_b32 s47, s46, 12
	s_lshl_b32 s44, s44, 7
	s_add_u32 s47, s47, s44
	s_lshl_b32 s47, s47, 11
	s_lshl_b32 s44, s45, 9
	s_add_u32 s47, s47, s44
	s_add_u32 s22, s38, s47
	s_addc_u32 s23, s39, 0
	s_waitcnt vmcnt(16)
	s_barrier
	s_branch .Lxa_loop
